# diff attention: the two P.V MFMAs sharing a V fragment issued in alternating order from fragment to fragment, so each MFMA changes only one input operand vs the previous one (23 independent pairs swap
# speedup vs baseline: 1.0174x; 1.0101x over previous
.LBB0_444:
	ds_read_b64_tr_b16 v[158:159], v203
	ds_read_b64_tr_b16 v[160:161], v203 offset:2048
	s_waitcnt lgkmcnt(9)
	v_mfma_f32_16x16x32_bf16 v[140:143], v[110:113], v[10:13], 0
	s_waitcnt lgkmcnt(7)
	v_mfma_f32_16x16x32_bf16 v[152:155], v[26:29], v[14:17], v[140:143]
	ds_read_b64_tr_b16 v[162:163], v204
	ds_read_b64_tr_b16 v[164:165], v204 offset:2048
	v_mfma_f32_16x16x32_bf16 v[110:113], v[110:113], v[18:21], 0
	v_mfma_f32_16x16x32_bf16 v[144:147], v[26:29], v[22:25], v[110:113]
	ds_read_b64_tr_b16 v[166:167], v205
	ds_read_b64_tr_b16 v[168:169], v205 offset:2048
	v_mfma_f32_16x16x32_bf16 v[26:29], v[116:119], v[10:13], 0
	s_waitcnt lgkmcnt(10)
	v_mfma_f32_16x16x32_bf16 v[148:151], v[120:123], v[14:17], v[26:29]
	ds_read_b64_tr_b16 v[170:171], v206
	ds_read_b64_tr_b16 v[172:173], v206 offset:2048
	v_mfma_f32_16x16x32_bf16 v[26:29], v[116:119], v[18:21], 0
	v_mfma_f32_16x16x32_bf16 v[140:143], v[120:123], v[22:25], v[26:29]
	ds_read_b64_tr_b16 v[174:175], v203 offset:8192
	ds_read_b64_tr_b16 v[176:177], v203 offset:10240
	s_waitcnt lgkmcnt(13)
	v_mfma_f32_16x16x32_bf16 v[26:29], v[124:127], v[10:13], 0
	s_waitcnt lgkmcnt(11)
	v_mfma_f32_16x16x32_bf16 v[110:113], v[132:135], v[14:17], v[26:29]
	ds_read_b64_tr_b16 v[208:209], v204 offset:8192
	ds_read_b64_tr_b16 v[210:211], v204 offset:10240
	v_mfma_f32_16x16x32_bf16 v[26:29], v[124:127], v[18:21], 0
	v_mfma_f32_16x16x32_bf16 v[116:119], v[132:135], v[22:25], v[26:29]
	ds_read_b64_tr_b16 v[132:133], v205 offset:8192
	ds_read_b64_tr_b16 v[134:135], v205 offset:10240
	v_mfma_f32_16x16x32_bf16 v[26:29], v[128:131], v[10:13], 0
	s_waitcnt lgkmcnt(14)
	v_mfma_f32_16x16x32_bf16 v[120:123], v[136:139], v[14:17], v[26:29]
	ds_read_b64_tr_b16 v[212:213], v206 offset:8192
	ds_read_b64_tr_b16 v[214:215], v206 offset:10240
	v_mfma_f32_16x16x32_bf16 v[26:29], v[128:131], v[18:21], 0
	v_mfma_f32_16x16x32_bf16 v[124:127], v[136:139], v[22:25], v[26:29]
	s_add_u32 s68, s14, 0xfcfe0000
	s_addc_u32 s69, s15, -1
	s_mov_b32 s74, m0
	s_mov_b32 m0, s30
	s_nop 0
	global_load_lds_dwordx4 v157, s[68:69]
	s_mov_b32 m0, s74
	s_add_u32 s68, s14, 0xfcfe0080
	s_addc_u32 s69, s15, -1
	s_mov_b32 s74, m0
	s_mov_b32 m0, s31
	s_nop 0
	global_load_lds_dwordx4 v157, s[68:69]
	s_mov_b32 m0, s74
	s_add_u32 s74, s14, 0xfffd0000
	s_addc_u32 s75, s15, -1
	s_add_i32 s68, s38, 0xc000
	s_mov_b32 s69, m0
	s_mov_b32 m0, s68
	s_nop 0
	global_load_lds_dwordx4 v156, s[74:75]
	s_mov_b32 m0, s69
	s_add_u32 s74, s14, 0xfffd0080
	s_addc_u32 s75, s15, -1
	s_add_i32 s69, s39, 0xc000
	s_mov_b32 s76, m0
	s_mov_b32 m0, s69
	s_nop 0
	global_load_lds_dwordx4 v156, s[74:75]
	s_mov_b32 m0, s76
	ds_read_b64_tr_b16 v[128:129], v203 offset:4096
	ds_read_b64_tr_b16 v[130:131], v203 offset:6144
	v_mov_b64_e32 v[28:29], s[6:7]
	v_mov_b64_e32 v[26:27], s[4:5]
	s_waitcnt lgkmcnt(14)
	v_mfma_f32_16x16x32_bf16 v[98:101], v[6:9], v[158:161], v[98:101]
	v_exp_f32_e32 v152, v152
	v_mfma_f32_16x16x32_bf16 v[106:109], v[6:9], v[26:29], v[106:109]
	v_mfma_f32_16x16x32_bf16 v[102:105], v[2:5], v[26:29], v[102:105]
	v_exp_f32_e32 v153, v153
	v_mfma_f32_16x16x32_bf16 v[90:93], v[2:5], v[158:161], v[90:93]
	ds_read_b64_tr_b16 v[136:137], v204 offset:4096
	ds_read_b64_tr_b16 v[138:139], v204 offset:6144
	v_mfma_f32_16x16x32_bf16 v[94:97], v[6:9], v[162:165], v[94:97]
	v_exp_f32_e32 v154, v154
	v_mfma_f32_16x16x32_bf16 v[82:85], v[2:5], v[162:165], v[82:85]
	v_exp_f32_e32 v155, v155
	ds_read_b64_tr_b16 v[158:159], v205 offset:4096
	ds_read_b64_tr_b16 v[160:161], v205 offset:6144
	s_waitcnt lgkmcnt(14)
	v_mfma_f32_16x16x32_bf16 v[162:165], v[2:5], v[166:169], v[74:77]
	v_exp_f32_e32 v144, v144
	s_nop 0
	v_exp_f32_e32 v145, v145
	v_mfma_f32_16x16x32_bf16 v[86:89], v[6:9], v[166:169], v[86:89]
	ds_read_b64_tr_b16 v[166:167], v206 offset:4096
	ds_read_b64_tr_b16 v[168:169], v206 offset:6144
	v_exp_f32_e32 v146, v146
	v_mfma_f32_16x16x32_bf16 v[216:219], v[6:9], v[170:173], v[78:81]
	s_nop 0
	v_exp_f32_e32 v147, v147
	v_mfma_f32_16x16x32_bf16 v[170:173], v[2:5], v[170:173], v[66:69]
	ds_read_b64_tr_b16 v[220:221], v203 offset:12288
	ds_read_b64_tr_b16 v[222:223], v203 offset:14336
	v_exp_f32_e32 v148, v148
	s_waitcnt lgkmcnt(14)
	v_mfma_f32_16x16x32_bf16 v[58:61], v[2:5], v[174:177], v[58:61]
	v_mfma_f32_16x16x32_bf16 v[224:227], v[6:9], v[174:177], v[70:73]
	v_exp_f32_e32 v149, v149
	ds_read_b64_tr_b16 v[174:175], v204 offset:12288
	ds_read_b64_tr_b16 v[176:177], v204 offset:14336
	v_exp_f32_e32 v150, v150
	v_mfma_f32_16x16x32_bf16 v[228:231], v[6:9], v[208:211], v[62:65]
	v_mfma_f32_16x16x32_bf16 v[50:53], v[2:5], v[208:211], v[50:53]
	v_exp_f32_e32 v151, v151
	ds_read_b64_tr_b16 v[208:209], v205 offset:12288
	ds_read_b64_tr_b16 v[210:211], v205 offset:14336
	s_waitcnt lgkmcnt(14)
	v_mfma_f32_16x16x32_bf16 v[42:45], v[2:5], v[132:135], v[42:45]
	v_exp_f32_e32 v140, v140
	v_mfma_f32_16x16x32_bf16 v[54:57], v[6:9], v[132:135], v[54:57]
	v_exp_f32_e32 v141, v141
	ds_read_b64_tr_b16 v[232:233], v206 offset:12288
	ds_read_b64_tr_b16 v[234:235], v206 offset:14336
	v_mfma_f32_16x16x32_bf16 v[46:49], v[6:9], v[212:215], v[46:49]
	v_exp_f32_e32 v142, v142
	s_nop 0
	v_exp_f32_e32 v143, v143
	v_mfma_f32_16x16x32_bf16 v[212:215], v[2:5], v[212:215], v[38:41]
	s_nop 2
	ds_read_b128 v[38:41], v1 offset:32768
	v_mfma_f32_16x16x32_bf16 v[66:69], v[34:37], v[26:29], v[106:109]
	v_exp_f32_e32 v110, v110
	v_cvt_pk_bf16_f32 v6, v152, v153
	s_waitcnt lgkmcnt(14)
	v_mfma_f32_16x16x32_bf16 v[62:65], v[34:37], v[128:131], v[98:101]
	v_mfma_f32_16x16x32_bf16 v[70:73], v[30:33], v[26:29], v[102:105]
	v_exp_f32_e32 v111, v111
	v_cvt_pk_bf16_f32 v7, v154, v155
	v_mfma_f32_16x16x32_bf16 v[78:81], v[30:33], v[128:131], v[90:93]
	ds_read_b128 v[236:239], v115 offset:32768
	s_waitcnt lgkmcnt(14)
	v_mfma_f32_16x16x32_bf16 v[82:85], v[30:33], v[136:139], v[82:85]
	v_exp_f32_e32 v112, v112
	v_cvt_pk_bf16_f32 v8, v148, v149
	v_mfma_f32_16x16x32_bf16 v[74:77], v[34:37], v[136:139], v[94:97]
	v_exp_f32_e32 v113, v113
	v_cvt_pk_bf16_f32 v9, v150, v151
	ds_read_b128 v[240:243], v1 offset:34816
	s_waitcnt lgkmcnt(13)
	v_mfma_f32_16x16x32_bf16 v[90:93], v[34:37], v[158:161], v[86:89]
	v_exp_f32_e32 v116, v116
	v_cvt_pk_bf16_f32 v2, v144, v145
	v_mfma_f32_16x16x32_bf16 v[94:97], v[30:33], v[158:161], v[162:165]
	v_exp_f32_e32 v117, v117
	v_cvt_pk_bf16_f32 v3, v146, v147
	ds_read_b128 v[158:161], v115 offset:34816
	s_waitcnt lgkmcnt(12)
	v_mfma_f32_16x16x32_bf16 v[102:105], v[30:33], v[166:169], v[170:173]
	v_exp_f32_e32 v118, v118
	v_cvt_pk_bf16_f32 v4, v140, v141
	v_mfma_f32_16x16x32_bf16 v[98:101], v[34:37], v[166:169], v[216:219]
	v_exp_f32_e32 v119, v119
	v_cvt_pk_bf16_f32 v5, v142, v143
	ds_read_b128 v[162:165], v1 offset:36864
	v_exp_f32_e32 v120, v120
	s_waitcnt lgkmcnt(11)
	v_mfma_f32_16x16x32_bf16 v[148:151], v[34:37], v[220:223], v[224:227]
	s_nop 0
	v_exp_f32_e32 v121, v121
	v_mfma_f32_16x16x32_bf16 v[152:155], v[30:33], v[220:223], v[58:61]
	ds_read_b128 v[166:169], v115 offset:36864
	v_exp_f32_e32 v122, v122
	s_waitcnt lgkmcnt(10)
	v_mfma_f32_16x16x32_bf16 v[144:147], v[30:33], v[174:177], v[50:53]
	s_nop 0
	v_exp_f32_e32 v123, v123
	v_mfma_f32_16x16x32_bf16 v[140:143], v[34:37], v[174:177], v[228:231]
	s_nop 2
	ds_read_b128 v[50:53], v1 offset:38912
	s_waitcnt lgkmcnt(9)
	v_mfma_f32_16x16x32_bf16 v[132:135], v[34:37], v[208:211], v[54:57]
	v_exp_f32_e32 v124, v124
	v_mfma_f32_16x16x32_bf16 v[136:139], v[30:33], v[208:211], v[42:45]
	v_exp_f32_e32 v125, v125
	ds_read_b128 v[170:173], v115 offset:38912
	s_waitcnt lgkmcnt(8)
	v_mfma_f32_16x16x32_bf16 v[128:131], v[30:33], v[232:235], v[212:215]
	v_exp_f32_e32 v126, v126
	v_mfma_f32_16x16x32_bf16 v[106:109], v[34:37], v[232:235], v[46:49]
	v_exp_f32_e32 v127, v127
	v_cvt_pk_bf16_f32 v34, v110, v111
	v_cvt_pk_bf16_f32 v35, v112, v113
	v_cvt_pk_bf16_f32 v36, v120, v121
	v_cvt_pk_bf16_f32 v37, v122, v123
	v_cvt_pk_bf16_f32 v30, v116, v117
	v_cvt_pk_bf16_f32 v31, v118, v119
	v_cvt_pk_bf16_f32 v32, v124, v125
	v_cvt_pk_bf16_f32 v33, v126, v127
	s_waitcnt vmcnt(4)
	s_barrier
	ds_read_b64_tr_b16 v[116:117], v203 offset:16384
	ds_read_b64_tr_b16 v[118:119], v203 offset:18432
	s_waitcnt lgkmcnt(9)
	v_mfma_f32_16x16x32_bf16 v[42:45], v[38:41], v[10:13], 0
	s_waitcnt lgkmcnt(8)
	v_mfma_f32_16x16x32_bf16 v[110:113], v[236:239], v[14:17], v[42:45]
	ds_read_b64_tr_b16 v[120:121], v204 offset:16384
	ds_read_b64_tr_b16 v[122:123], v204 offset:18432
	v_mfma_f32_16x16x32_bf16 v[38:41], v[38:41], v[18:21], 0
	v_mfma_f32_16x16x32_bf16 v[58:61], v[236:239], v[22:25], v[38:41]
	ds_read_b64_tr_b16 v[124:125], v205 offset:16384
	ds_read_b64_tr_b16 v[126:127], v205 offset:18432
	s_waitcnt lgkmcnt(11)
	v_mfma_f32_16x16x32_bf16 v[38:41], v[240:243], v[10:13], 0
	s_waitcnt lgkmcnt(10)
	v_mfma_f32_16x16x32_bf16 v[86:89], v[158:161], v[14:17], v[38:41]
	ds_read_b64_tr_b16 v[174:175], v206 offset:16384
	ds_read_b64_tr_b16 v[176:177], v206 offset:18432
	v_mfma_f32_16x16x32_bf16 v[38:41], v[240:243], v[18:21], 0
	v_mfma_f32_16x16x32_bf16 v[54:57], v[158:161], v[22:25], v[38:41]
	ds_read_b64_tr_b16 v[158:159], v203 offset:24576
	ds_read_b64_tr_b16 v[160:161], v203 offset:26624
	s_waitcnt lgkmcnt(13)
	v_mfma_f32_16x16x32_bf16 v[38:41], v[162:165], v[10:13], 0
	s_waitcnt lgkmcnt(12)
	v_mfma_f32_16x16x32_bf16 v[38:41], v[166:169], v[14:17], v[38:41]
	ds_read_b64_tr_b16 v[208:209], v204 offset:24576
	ds_read_b64_tr_b16 v[210:211], v204 offset:26624
	v_mfma_f32_16x16x32_bf16 v[42:45], v[162:165], v[18:21], 0
	v_mfma_f32_16x16x32_bf16 v[42:45], v[166:169], v[22:25], v[42:45]
	ds_read_b64_tr_b16 v[162:163], v205 offset:24576
	ds_read_b64_tr_b16 v[164:165], v205 offset:26624
	s_waitcnt lgkmcnt(14)
	v_mfma_f32_16x16x32_bf16 v[46:49], v[50:53], v[10:13], 0
	v_mfma_f32_16x16x32_bf16 v[46:49], v[170:173], v[14:17], v[46:49]
	ds_read_b64_tr_b16 v[166:167], v206 offset:24576
	ds_read_b64_tr_b16 v[168:169], v206 offset:26624
	v_mfma_f32_16x16x32_bf16 v[50:53], v[50:53], v[18:21], 0
	v_mfma_f32_16x16x32_bf16 v[50:53], v[170:173], v[22:25], v[50:53]
	s_add_u32 s74, s14, 0xfcff0000
	s_addc_u32 s75, s15, -1
	s_mov_b32 s76, m0
	s_mov_b32 m0, s40
	s_nop 0
	global_load_lds_dwordx4 v157, s[74:75]
	s_mov_b32 m0, s76
	s_add_u32 s74, s14, 0xfcff0080
	s_addc_u32 s75, s15, -1
	s_mov_b32 s76, m0
	s_mov_b32 m0, s41
	s_nop 0
	global_load_lds_dwordx4 v157, s[74:75]
	s_mov_b32 m0, s76
	s_add_u32 s74, s14, 0xfffe0000
	s_addc_u32 s75, s15, -1
	s_mov_b32 s76, m0
	s_mov_b32 m0, s38
	s_nop 0
	global_load_lds_dwordx4 v156, s[74:75]
	s_mov_b32 m0, s76
	s_add_u32 s74, s14, 0xfffe0080
	s_addc_u32 s75, s15, -1
	s_mov_b32 s76, m0
	s_mov_b32 m0, s39
	s_nop 0
	global_load_lds_dwordx4 v156, s[74:75]
	s_mov_b32 m0, s76
	ds_read_b64_tr_b16 v[170:171], v203 offset:20480
	ds_read_b64_tr_b16 v[172:173], v203 offset:22528
	v_mfma_f32_16x16x32_bf16 v[66:69], v[6:9], v[26:29], v[66:69]
	v_exp_f32_e32 v110, v110
	s_waitcnt lgkmcnt(14)
	v_mfma_f32_16x16x32_bf16 v[62:65], v[6:9], v[116:119], v[62:65]
	v_mfma_f32_16x16x32_bf16 v[70:73], v[2:5], v[26:29], v[70:73]
	v_exp_f32_e32 v111, v111
	v_mfma_f32_16x16x32_bf16 v[78:81], v[2:5], v[116:119], v[78:81]
	ds_read_b64_tr_b16 v[116:117], v204 offset:20480
	ds_read_b64_tr_b16 v[118:119], v204 offset:22528
	v_mfma_f32_16x16x32_bf16 v[74:77], v[6:9], v[120:123], v[74:77]
	v_exp_f32_e32 v112, v112
	v_mfma_f32_16x16x32_bf16 v[82:85], v[2:5], v[120:123], v[82:85]
	v_exp_f32_e32 v113, v113
	ds_read_b64_tr_b16 v[120:121], v205 offset:20480
	ds_read_b64_tr_b16 v[122:123], v205 offset:22528
	s_waitcnt lgkmcnt(14)
	v_mfma_f32_16x16x32_bf16 v[94:97], v[2:5], v[124:127], v[94:97]
	v_exp_f32_e32 v58, v58
	v_mfma_f32_16x16x32_bf16 v[90:93], v[6:9], v[124:127], v[90:93]
	v_exp_f32_e32 v59, v59
	ds_read_b64_tr_b16 v[124:125], v206 offset:20480
	ds_read_b64_tr_b16 v[126:127], v206 offset:22528
	v_mfma_f32_16x16x32_bf16 v[98:101], v[6:9], v[174:177], v[98:101]
	v_exp_f32_e32 v60, v60
	v_mfma_f32_16x16x32_bf16 v[102:105], v[2:5], v[174:177], v[102:105]
	v_exp_f32_e32 v61, v61
	ds_read_b64_tr_b16 v[174:175], v203 offset:28672
	ds_read_b64_tr_b16 v[176:177], v203 offset:30720
	v_exp_f32_e32 v86, v86
	s_waitcnt lgkmcnt(14)
	v_mfma_f32_16x16x32_bf16 v[152:155], v[2:5], v[158:161], v[152:155]
	s_nop 0
	v_exp_f32_e32 v87, v87
	v_mfma_f32_16x16x32_bf16 v[148:151], v[6:9], v[158:161], v[148:151]
	ds_read_b64_tr_b16 v[158:159], v204 offset:28672
	ds_read_b64_tr_b16 v[160:161], v204 offset:30720
	v_exp_f32_e32 v88, v88
	v_mfma_f32_16x16x32_bf16 v[212:215], v[6:9], v[208:211], v[140:143]
	s_nop 0
	v_exp_f32_e32 v89, v89
	v_mfma_f32_16x16x32_bf16 v[208:211], v[2:5], v[208:211], v[144:147]
	ds_read_b64_tr_b16 v[216:217], v205 offset:28672
	ds_read_b64_tr_b16 v[218:219], v205 offset:30720
	v_exp_f32_e32 v54, v54
	s_waitcnt lgkmcnt(14)
	v_mfma_f32_16x16x32_bf16 v[220:223], v[6:9], v[162:165], v[132:135]
	s_nop 0
	v_exp_f32_e32 v55, v55
	v_mfma_f32_16x16x32_bf16 v[162:165], v[2:5], v[162:165], v[136:139]
	ds_read_b64_tr_b16 v[224:225], v206 offset:28672
	ds_read_b64_tr_b16 v[226:227], v206 offset:30720
	v_mfma_f32_16x16x32_bf16 v[106:109], v[6:9], v[166:169], v[106:109]
	v_exp_f32_e32 v56, v56
	s_nop 0
	v_exp_f32_e32 v57, v57
	v_mfma_f32_16x16x32_bf16 v[166:169], v[2:5], v[166:169], v[128:131]
	ds_read_b128 v[144:147], v1 offset:49152
	v_mfma_f32_16x16x32_bf16 v[66:69], v[34:37], v[26:29], v[66:69]
	v_exp_f32_e32 v38, v38
	v_cvt_pk_bf16_f32 v6, v110, v111
	s_waitcnt lgkmcnt(14)
	v_mfma_f32_16x16x32_bf16 v[62:65], v[34:37], v[170:173], v[62:65]
	v_mfma_f32_16x16x32_bf16 v[70:73], v[30:33], v[26:29], v[70:73]
	v_exp_f32_e32 v39, v39
	v_cvt_pk_bf16_f32 v7, v112, v113
	v_mfma_f32_16x16x32_bf16 v[78:81], v[30:33], v[170:173], v[78:81]
	ds_read_b128 v[170:173], v115 offset:49152
	s_waitcnt lgkmcnt(14)
	v_mfma_f32_16x16x32_bf16 v[82:85], v[30:33], v[116:119], v[82:85]
	v_exp_f32_e32 v40, v40
	v_cvt_pk_bf16_f32 v8, v86, v87
	v_mfma_f32_16x16x32_bf16 v[74:77], v[34:37], v[116:119], v[74:77]
	v_exp_f32_e32 v41, v41
	v_cvt_pk_bf16_f32 v9, v88, v89
	ds_read_b128 v[228:231], v1 offset:51200
	s_waitcnt lgkmcnt(13)
	v_mfma_f32_16x16x32_bf16 v[90:93], v[34:37], v[120:123], v[90:93]
	v_exp_f32_e32 v42, v42
	v_cvt_pk_bf16_f32 v2, v58, v59
	v_mfma_f32_16x16x32_bf16 v[94:97], v[30:33], v[120:123], v[94:97]
	v_exp_f32_e32 v43, v43
	v_cvt_pk_bf16_f32 v3, v60, v61
	ds_read_b128 v[232:235], v115 offset:51200
	s_waitcnt lgkmcnt(12)
	v_mfma_f32_16x16x32_bf16 v[102:105], v[30:33], v[124:127], v[102:105]
	v_exp_f32_e32 v44, v44
	v_cvt_pk_bf16_f32 v4, v54, v55
	v_mfma_f32_16x16x32_bf16 v[98:101], v[34:37], v[124:127], v[98:101]
	v_exp_f32_e32 v45, v45
	v_cvt_pk_bf16_f32 v5, v56, v57
	ds_read_b128 v[236:239], v1 offset:53248
	s_waitcnt lgkmcnt(11)
	v_mfma_f32_16x16x32_bf16 v[136:139], v[34:37], v[174:177], v[148:151]
	v_exp_f32_e32 v46, v46
	s_nop 0
	v_exp_f32_e32 v47, v47
	v_mfma_f32_16x16x32_bf16 v[140:143], v[30:33], v[174:177], v[152:155]
	ds_read_b128 v[148:151], v115 offset:53248
	s_waitcnt lgkmcnt(10)
	v_mfma_f32_16x16x32_bf16 v[132:135], v[30:33], v[158:161], v[208:211]
	v_exp_f32_e32 v48, v48
	v_mfma_f32_16x16x32_bf16 v[128:131], v[34:37], v[158:161], v[212:215]
	v_exp_f32_e32 v49, v49
	ds_read_b128 v[152:155], v1 offset:55296
	s_waitcnt lgkmcnt(9)
	v_mfma_f32_16x16x32_bf16 v[120:123], v[34:37], v[216:219], v[220:223]
	v_exp_f32_e32 v50, v50
	v_mfma_f32_16x16x32_bf16 v[124:127], v[30:33], v[216:219], v[162:165]
	v_exp_f32_e32 v51, v51
	ds_read_b128 v[158:161], v115 offset:55296
	s_waitcnt lgkmcnt(8)
	v_mfma_f32_16x16x32_bf16 v[110:113], v[30:33], v[224:227], v[166:169]
	v_exp_f32_e32 v52, v52
	v_mfma_f32_16x16x32_bf16 v[106:109], v[34:37], v[224:227], v[106:109]
	v_exp_f32_e32 v53, v53
	v_cvt_pk_bf16_f32 v34, v38, v39
	v_cvt_pk_bf16_f32 v35, v40, v41
	v_cvt_pk_bf16_f32 v36, v46, v47
	v_cvt_pk_bf16_f32 v37, v48, v49
	v_cvt_pk_bf16_f32 v30, v42, v43
	v_cvt_pk_bf16_f32 v31, v44, v45
	v_cvt_pk_bf16_f32 v32, v50, v51
	v_cvt_pk_bf16_f32 v33, v52, v53
	s_waitcnt vmcnt(4)
	s_barrier
	ds_read_b64_tr_b16 v[162:163], v203 offset:32768
	ds_read_b64_tr_b16 v[164:165], v203 offset:34816
	s_waitcnt lgkmcnt(9)
	v_mfma_f32_16x16x32_bf16 v[38:41], v[144:147], v[10:13], 0
	s_waitcnt lgkmcnt(8)
	v_mfma_f32_16x16x32_bf16 v[116:119], v[170:173], v[14:17], v[38:41]
	ds_read_b64_tr_b16 v[166:167], v204 offset:32768
	ds_read_b64_tr_b16 v[168:169], v204 offset:34816
	v_mfma_f32_16x16x32_bf16 v[38:41], v[144:147], v[18:21], 0
	v_mfma_f32_16x16x32_bf16 v[58:61], v[170:173], v[22:25], v[38:41]
	ds_read_b64_tr_b16 v[144:145], v205 offset:32768
	ds_read_b64_tr_b16 v[146:147], v205 offset:34816
	s_waitcnt lgkmcnt(11)
	v_mfma_f32_16x16x32_bf16 v[38:41], v[228:231], v[10:13], 0
	s_waitcnt lgkmcnt(10)
	v_mfma_f32_16x16x32_bf16 v[86:89], v[232:235], v[14:17], v[38:41]
	ds_read_b64_tr_b16 v[170:171], v206 offset:32768
	ds_read_b64_tr_b16 v[172:173], v206 offset:34816
	v_mfma_f32_16x16x32_bf16 v[38:41], v[228:231], v[18:21], 0
	v_mfma_f32_16x16x32_bf16 v[54:57], v[232:235], v[22:25], v[38:41]
	ds_read_b64_tr_b16 v[174:175], v203 offset:40960
	ds_read_b64_tr_b16 v[176:177], v203 offset:43008
	s_waitcnt lgkmcnt(13)
	v_mfma_f32_16x16x32_bf16 v[38:41], v[236:239], v[10:13], 0
	s_waitcnt lgkmcnt(12)
	v_mfma_f32_16x16x32_bf16 v[38:41], v[148:151], v[14:17], v[38:41]
	ds_read_b64_tr_b16 v[208:209], v204 offset:40960
	ds_read_b64_tr_b16 v[210:211], v204 offset:43008
	v_mfma_f32_16x16x32_bf16 v[42:45], v[236:239], v[18:21], 0
	v_mfma_f32_16x16x32_bf16 v[42:45], v[148:151], v[22:25], v[42:45]
	ds_read_b64_tr_b16 v[148:149], v205 offset:40960
	ds_read_b64_tr_b16 v[150:151], v205 offset:43008
	s_waitcnt lgkmcnt(14)
	v_mfma_f32_16x16x32_bf16 v[46:49], v[152:155], v[10:13], 0
	v_mfma_f32_16x16x32_bf16 v[46:49], v[158:161], v[14:17], v[46:49]
	ds_read_b64_tr_b16 v[212:213], v206 offset:40960
	ds_read_b64_tr_b16 v[214:215], v206 offset:43008
	v_mfma_f32_16x16x32_bf16 v[50:53], v[152:155], v[18:21], 0
	v_mfma_f32_16x16x32_bf16 v[50:53], v[158:161], v[22:25], v[50:53]
	s_add_u32 s74, s14, 0xfd000000
	s_addc_u32 s75, s15, -1
	s_mov_b32 s76, m0
	s_mov_b32 m0, s52
	s_nop 0
	global_load_lds_dwordx4 v157, s[74:75]
	s_mov_b32 m0, s76
	s_add_u32 s74, s14, 0xfd000080
	s_addc_u32 s75, s15, -1
	s_mov_b32 s76, m0
	s_mov_b32 m0, s53
	s_nop 0
	global_load_lds_dwordx4 v157, s[74:75]
	s_mov_b32 m0, s76
	s_add_u32 s74, s14, 0xffff0000
	s_addc_u32 s75, s15, -1
	s_mov_b32 s76, m0
	s_mov_b32 m0, s62
	s_nop 0
	global_load_lds_dwordx4 v156, s[74:75]
	s_mov_b32 m0, s76
	s_add_u32 s74, s14, 0xffff0080
	s_addc_u32 s75, s15, -1
	s_mov_b32 s76, m0
	s_mov_b32 m0, s63
	s_nop 0
	global_load_lds_dwordx4 v156, s[74:75]
	s_mov_b32 m0, s76
	ds_read_b64_tr_b16 v[152:153], v203 offset:36864
	ds_read_b64_tr_b16 v[154:155], v203 offset:38912
	v_mfma_f32_16x16x32_bf16 v[66:69], v[6:9], v[26:29], v[66:69]
	v_exp_f32_e32 v116, v116
	s_waitcnt lgkmcnt(14)
	v_mfma_f32_16x16x32_bf16 v[62:65], v[6:9], v[162:165], v[62:65]
	v_mfma_f32_16x16x32_bf16 v[70:73], v[2:5], v[26:29], v[70:73]
	v_exp_f32_e32 v117, v117
	v_mfma_f32_16x16x32_bf16 v[78:81], v[2:5], v[162:165], v[78:81]
	ds_read_b64_tr_b16 v[158:159], v204 offset:36864
	ds_read_b64_tr_b16 v[160:161], v204 offset:38912
	v_mfma_f32_16x16x32_bf16 v[74:77], v[6:9], v[166:169], v[74:77]
	v_exp_f32_e32 v118, v118
	v_mfma_f32_16x16x32_bf16 v[82:85], v[2:5], v[166:169], v[82:85]
	v_exp_f32_e32 v119, v119
	ds_read_b64_tr_b16 v[162:163], v205 offset:36864
	ds_read_b64_tr_b16 v[164:165], v205 offset:38912
	s_waitcnt lgkmcnt(14)
	v_mfma_f32_16x16x32_bf16 v[94:97], v[2:5], v[144:147], v[94:97]
	v_exp_f32_e32 v58, v58
	v_mfma_f32_16x16x32_bf16 v[90:93], v[6:9], v[144:147], v[90:93]
	v_exp_f32_e32 v59, v59
	ds_read_b64_tr_b16 v[144:145], v206 offset:36864
	ds_read_b64_tr_b16 v[146:147], v206 offset:38912
	v_mfma_f32_16x16x32_bf16 v[98:101], v[6:9], v[170:173], v[98:101]
	v_exp_f32_e32 v60, v60
	v_mfma_f32_16x16x32_bf16 v[102:105], v[2:5], v[170:173], v[102:105]
	v_exp_f32_e32 v61, v61
	ds_read_b64_tr_b16 v[166:167], v203 offset:45056
	ds_read_b64_tr_b16 v[168:169], v203 offset:47104
	s_waitcnt lgkmcnt(14)
	v_mfma_f32_16x16x32_bf16 v[140:143], v[2:5], v[174:177], v[140:143]
	v_exp_f32_e32 v86, v86
	s_nop 0
	v_exp_f32_e32 v87, v87
	v_mfma_f32_16x16x32_bf16 v[136:139], v[6:9], v[174:177], v[136:139]
	ds_read_b64_tr_b16 v[170:171], v204 offset:45056
	ds_read_b64_tr_b16 v[172:173], v204 offset:47104
	v_exp_f32_e32 v88, v88
	v_mfma_f32_16x16x32_bf16 v[174:177], v[6:9], v[208:211], v[128:131]
	v_mfma_f32_16x16x32_bf16 v[132:135], v[2:5], v[208:211], v[132:135]
	v_exp_f32_e32 v89, v89
	ds_read_b64_tr_b16 v[208:209], v205 offset:45056
	ds_read_b64_tr_b16 v[210:211], v205 offset:47104
	v_exp_f32_e32 v54, v54
	s_waitcnt lgkmcnt(14)
	v_mfma_f32_16x16x32_bf16 v[216:219], v[6:9], v[148:151], v[120:123]
	s_nop 0
	v_exp_f32_e32 v55, v55
	v_mfma_f32_16x16x32_bf16 v[148:151], v[2:5], v[148:151], v[124:127]
	ds_read_b64_tr_b16 v[220:221], v206 offset:45056
	ds_read_b64_tr_b16 v[222:223], v206 offset:47104
	v_exp_f32_e32 v56, v56
	v_mfma_f32_16x16x32_bf16 v[224:227], v[6:9], v[212:215], v[106:109]
	s_nop 0
	v_exp_f32_e32 v57, v57
	v_mfma_f32_16x16x32_bf16 v[212:215], v[2:5], v[212:215], v[110:113]
	ds_read_b128 v[128:131], v1
	v_mfma_f32_16x16x32_bf16 v[66:69], v[34:37], v[26:29], v[66:69]
	v_exp_f32_e32 v38, v38
	v_cvt_pk_bf16_f32 v6, v116, v117
	s_waitcnt lgkmcnt(14)
	v_mfma_f32_16x16x32_bf16 v[62:65], v[34:37], v[152:155], v[62:65]
	v_mfma_f32_16x16x32_bf16 v[70:73], v[30:33], v[26:29], v[70:73]
	v_exp_f32_e32 v39, v39
	v_cvt_pk_bf16_f32 v7, v118, v119
	v_mfma_f32_16x16x32_bf16 v[78:81], v[30:33], v[152:155], v[78:81]
	ds_read_b128 v[152:155], v115
	s_waitcnt lgkmcnt(14)
	v_mfma_f32_16x16x32_bf16 v[82:85], v[30:33], v[158:161], v[82:85]
	v_exp_f32_e32 v40, v40
	v_cvt_pk_bf16_f32 v8, v86, v87
	v_mfma_f32_16x16x32_bf16 v[74:77], v[34:37], v[158:161], v[74:77]
	v_exp_f32_e32 v41, v41
	v_cvt_pk_bf16_f32 v9, v88, v89
	ds_read_b128 v[158:161], v1 offset:2048
	s_waitcnt lgkmcnt(13)
	v_mfma_f32_16x16x32_bf16 v[86:89], v[34:37], v[162:165], v[90:93]
	v_exp_f32_e32 v42, v42
	v_cvt_pk_bf16_f32 v2, v58, v59
	v_mfma_f32_16x16x32_bf16 v[90:93], v[30:33], v[162:165], v[94:97]
	v_exp_f32_e32 v43, v43
	v_cvt_pk_bf16_f32 v3, v60, v61
	ds_read_b128 v[162:165], v115 offset:2048
	s_waitcnt lgkmcnt(12)
	v_mfma_f32_16x16x32_bf16 v[94:97], v[30:33], v[144:147], v[102:105]
	v_exp_f32_e32 v44, v44
	v_cvt_pk_bf16_f32 v4, v54, v55
	v_mfma_f32_16x16x32_bf16 v[58:61], v[34:37], v[144:147], v[98:101]
	v_exp_f32_e32 v45, v45
	v_cvt_pk_bf16_f32 v5, v56, v57
	ds_read_b128 v[144:147], v1 offset:4096
	s_waitcnt lgkmcnt(11)
	v_mfma_f32_16x16x32_bf16 v[120:123], v[34:37], v[166:169], v[136:139]
	v_exp_f32_e32 v46, v46
	v_mfma_f32_16x16x32_bf16 v[124:127], v[30:33], v[166:169], v[140:143]
	v_exp_f32_e32 v47, v47
	ds_read_b128 v[136:139], v115 offset:4096
	s_waitcnt lgkmcnt(10)
	v_mfma_f32_16x16x32_bf16 v[116:119], v[30:33], v[170:173], v[132:135]
	v_exp_f32_e32 v48, v48
	v_mfma_f32_16x16x32_bf16 v[110:113], v[34:37], v[170:173], v[174:177]
	v_exp_f32_e32 v49, v49
	s_nop 1
	ds_read_b128 v[132:135], v1 offset:6144
	s_waitcnt lgkmcnt(9)
	v_mfma_f32_16x16x32_bf16 v[102:105], v[34:37], v[208:211], v[216:219]
	v_exp_f32_e32 v50, v50
	v_mfma_f32_16x16x32_bf16 v[106:109], v[30:33], v[208:211], v[148:151]
	v_exp_f32_e32 v51, v51
	ds_read_b128 v[166:169], v115 offset:6144
	s_waitcnt lgkmcnt(8)
	v_mfma_f32_16x16x32_bf16 v[98:101], v[30:33], v[220:223], v[212:215]
	v_exp_f32_e32 v52, v52
	v_mfma_f32_16x16x32_bf16 v[54:57], v[34:37], v[220:223], v[224:227]
	v_exp_f32_e32 v53, v53
	v_cvt_pk_bf16_f32 v34, v38, v39
	v_cvt_pk_bf16_f32 v35, v40, v41
	v_cvt_pk_bf16_f32 v36, v46, v47
	v_cvt_pk_bf16_f32 v37, v48, v49
	v_cvt_pk_bf16_f32 v30, v42, v43
	v_cvt_pk_bf16_f32 v31, v44, v45
	v_cvt_pk_bf16_f32 v32, v50, v51
	v_cvt_pk_bf16_f32 v33, v52, v53
	s_waitcnt vmcnt(4)
	s_barrier
	ds_read_b64_tr_b16 v[170:171], v203 offset:49152
	ds_read_b64_tr_b16 v[172:173], v203 offset:51200
	s_waitcnt lgkmcnt(9)
	v_mfma_f32_16x16x32_bf16 v[38:41], v[128:131], v[10:13], 0
	s_waitcnt lgkmcnt(8)
	v_mfma_f32_16x16x32_bf16 v[50:53], v[152:155], v[14:17], v[38:41]
	ds_read_b64_tr_b16 v[174:175], v204 offset:49152
	ds_read_b64_tr_b16 v[176:177], v204 offset:51200
	v_mfma_f32_16x16x32_bf16 v[38:41], v[128:131], v[18:21], 0
	v_mfma_f32_16x16x32_bf16 v[42:45], v[152:155], v[22:25], v[38:41]
	ds_read_b64_tr_b16 v[128:129], v205 offset:49152
	ds_read_b64_tr_b16 v[130:131], v205 offset:51200
	s_waitcnt lgkmcnt(11)
	v_mfma_f32_16x16x32_bf16 v[38:41], v[158:161], v[10:13], 0
	s_waitcnt lgkmcnt(10)
	v_mfma_f32_16x16x32_bf16 v[46:49], v[162:165], v[14:17], v[38:41]
	ds_read_b64_tr_b16 v[208:209], v206 offset:49152
	ds_read_b64_tr_b16 v[210:211], v206 offset:51200
	v_mfma_f32_16x16x32_bf16 v[38:41], v[158:161], v[18:21], 0
	v_mfma_f32_16x16x32_bf16 v[38:41], v[162:165], v[22:25], v[38:41]
	ds_read_b64_tr_b16 v[158:159], v203 offset:57344
	ds_read_b64_tr_b16 v[160:161], v203 offset:59392
	s_waitcnt lgkmcnt(13)
	v_mfma_f32_16x16x32_bf16 v[140:143], v[144:147], v[10:13], 0
	s_waitcnt lgkmcnt(12)
	v_mfma_f32_16x16x32_bf16 v[140:143], v[136:139], v[14:17], v[140:143]
	ds_read_b64_tr_b16 v[162:163], v204 offset:57344
	ds_read_b64_tr_b16 v[164:165], v204 offset:59392
	v_mfma_f32_16x16x32_bf16 v[144:147], v[144:147], v[18:21], 0
	v_mfma_f32_16x16x32_bf16 v[144:147], v[136:139], v[22:25], v[144:147]
	ds_read_b64_tr_b16 v[136:137], v205 offset:57344
	ds_read_b64_tr_b16 v[138:139], v205 offset:59392
	s_waitcnt lgkmcnt(14)
	v_mfma_f32_16x16x32_bf16 v[148:151], v[132:135], v[10:13], 0
	v_mfma_f32_16x16x32_bf16 v[148:151], v[166:169], v[14:17], v[148:151]
	ds_read_b64_tr_b16 v[212:213], v206 offset:57344
	ds_read_b64_tr_b16 v[214:215], v206 offset:59392
	v_mfma_f32_16x16x32_bf16 v[132:135], v[132:135], v[18:21], 0
	v_mfma_f32_16x16x32_bf16 v[152:155], v[166:169], v[22:25], v[132:135]
	s_add_u32 s74, s14, 0xfd010000
	s_addc_u32 s75, s15, -1
	s_mov_b32 s76, m0
	s_mov_b32 m0, s66
	s_nop 0
	global_load_lds_dwordx4 v157, s[74:75]
	s_mov_b32 m0, s76
	s_add_u32 s74, s14, 0xfd010080
	s_addc_u32 s75, s15, -1
	s_mov_b32 s76, m0
	s_mov_b32 m0, s28
	s_nop 0
	global_load_lds_dwordx4 v157, s[74:75]
	s_mov_b32 m0, s76
	s_mov_b32 s74, m0
	s_mov_b32 m0, s29
	s_nop 0
	global_load_lds_dwordx4 v156, s[14:15]
	s_mov_b32 m0, s74
	s_add_u32 s74, s14, 0x80
	s_addc_u32 s75, s15, 0
	s_mov_b32 s76, m0
	s_mov_b32 m0, s67
	s_nop 0
	global_load_lds_dwordx4 v156, s[74:75]
	s_mov_b32 m0, s76
	s_nop 0
	ds_read_b64_tr_b16 v[132:133], v203 offset:53248
	ds_read_b64_tr_b16 v[134:135], v203 offset:55296
	v_mfma_f32_16x16x32_bf16 v[66:69], v[6:9], v[26:29], v[66:69]
	v_exp_f32_e32 v50, v50
	s_waitcnt lgkmcnt(14)
	v_mfma_f32_16x16x32_bf16 v[62:65], v[6:9], v[170:173], v[62:65]
	v_mfma_f32_16x16x32_bf16 v[70:73], v[2:5], v[26:29], v[70:73]
	v_exp_f32_e32 v51, v51
	v_mfma_f32_16x16x32_bf16 v[78:81], v[2:5], v[170:173], v[78:81]
	ds_read_b64_tr_b16 v[166:167], v204 offset:53248
	ds_read_b64_tr_b16 v[168:169], v204 offset:55296
	v_mfma_f32_16x16x32_bf16 v[74:77], v[6:9], v[174:177], v[74:77]
	v_exp_f32_e32 v52, v52
	v_mfma_f32_16x16x32_bf16 v[82:85], v[2:5], v[174:177], v[82:85]
	v_exp_f32_e32 v53, v53
	ds_read_b64_tr_b16 v[170:171], v205 offset:53248
	ds_read_b64_tr_b16 v[172:173], v205 offset:55296
	s_waitcnt lgkmcnt(14)
; #define ATT_WAIT_BARV(N) asm volatile("s_waitcnt vmcnt(" #N ")\n\ts_barrier" ::: "memory")
; __device__ __forceinline__ void attn_unit_d16(const UnitDesc& U, char* shm, float lam, const float* subw) {
;     ...
;     for (int t = 1; t <= NT - 4; t += 4) {
;         STEP_D16(t, true, true, true, 1, 2, 0, 0, 3);     ATT_WAIT_BARV(4);
;         STEP_D16(t + 1, true, true, true, 2, 3, 1, 1, 0); ATT_WAIT_BARV(4);
;         STEP_D16(t + 2, true, true, true, 3, 0, 2, 2, 1); ATT_WAIT_BARV(4);
;         STEP_D16(t + 3, true, true, true, 0, 1, 3, 3, 2); ATT_WAIT_BARV(4);
;     }
	v_mfma_f32_16x16x32_bf16 v[86:89], v[6:9], v[128:131], v[86:89]
	v_exp_f32_e32 v42, v42
	v_mfma_f32_16x16x32_bf16 v[128:131], v[2:5], v[128:131], v[90:93]
	v_exp_f32_e32 v43, v43
	ds_read_b64_tr_b16 v[174:175], v206 offset:53248
	ds_read_b64_tr_b16 v[176:177], v206 offset:55296
	v_mfma_f32_16x16x32_bf16 v[58:61], v[6:9], v[208:211], v[58:61]
	v_exp_f32_e32 v44, v44
	s_nop 0
	v_exp_f32_e32 v45, v45
	v_mfma_f32_16x16x32_bf16 v[208:211], v[2:5], v[208:211], v[94:97]
	ds_read_b64_tr_b16 v[216:217], v203 offset:61440
	ds_read_b64_tr_b16 v[218:219], v203 offset:63488
	v_exp_f32_e32 v46, v46
	s_waitcnt lgkmcnt(14)
	v_mfma_f32_16x16x32_bf16 v[220:223], v[6:9], v[158:161], v[120:123]
	s_nop 0
	v_exp_f32_e32 v47, v47
	v_mfma_f32_16x16x32_bf16 v[158:161], v[2:5], v[158:161], v[124:127]
	ds_read_b64_tr_b16 v[224:225], v204 offset:61440
	ds_read_b64_tr_b16 v[226:227], v204 offset:63488
	v_exp_f32_e32 v48, v48
	v_mfma_f32_16x16x32_bf16 v[228:231], v[6:9], v[162:165], v[110:113]
	s_nop 0
	v_exp_f32_e32 v49, v49
	v_mfma_f32_16x16x32_bf16 v[162:165], v[2:5], v[162:165], v[116:119]
	ds_read_b64_tr_b16 v[232:233], v205 offset:61440
	ds_read_b64_tr_b16 v[234:235], v205 offset:63488
	v_exp_f32_e32 v38, v38
	s_waitcnt lgkmcnt(14)
	v_mfma_f32_16x16x32_bf16 v[236:239], v[6:9], v[136:139], v[102:105]
	v_mfma_f32_16x16x32_bf16 v[136:139], v[2:5], v[136:139], v[106:109]
	v_exp_f32_e32 v39, v39
	ds_read_b64_tr_b16 v[240:241], v206 offset:61440
	ds_read_b64_tr_b16 v[242:243], v206 offset:63488
	v_exp_f32_e32 v40, v40
	v_mfma_f32_16x16x32_bf16 v[244:247], v[6:9], v[212:215], v[54:57]
	s_nop 0
	v_exp_f32_e32 v41, v41
	v_mfma_f32_16x16x32_bf16 v[212:215], v[2:5], v[212:215], v[98:101]
	ds_read_b128 v[110:113], v1 offset:16384
	v_mfma_f32_16x16x32_bf16 v[106:109], v[34:37], v[26:29], v[66:69]
	v_exp_f32_e32 v140, v140
	v_cvt_pk_bf16_f32 v6, v50, v51
	s_waitcnt lgkmcnt(14)
	v_mfma_f32_16x16x32_bf16 v[98:101], v[34:37], v[132:135], v[62:65]
	v_mfma_f32_16x16x32_bf16 v[102:105], v[30:33], v[26:29], v[70:73]
	v_exp_f32_e32 v141, v141
	v_cvt_pk_bf16_f32 v7, v52, v53
	v_mfma_f32_16x16x32_bf16 v[90:93], v[30:33], v[132:135], v[78:81]
	ds_read_b128 v[26:29], v115 offset:16384
	s_waitcnt lgkmcnt(14)
	v_mfma_f32_16x16x32_bf16 v[82:85], v[30:33], v[166:169], v[82:85]
	v_exp_f32_e32 v142, v142
	v_cvt_pk_bf16_f32 v8, v46, v47
	v_mfma_f32_16x16x32_bf16 v[94:97], v[34:37], v[166:169], v[74:77]
	v_exp_f32_e32 v143, v143
	v_cvt_pk_bf16_f32 v9, v48, v49
	ds_read_b128 v[116:119], v1 offset:18432
	s_waitcnt lgkmcnt(13)
	v_mfma_f32_16x16x32_bf16 v[86:89], v[34:37], v[170:173], v[86:89]
	v_exp_f32_e32 v144, v144
	v_cvt_pk_bf16_f32 v2, v42, v43
	v_mfma_f32_16x16x32_bf16 v[74:77], v[30:33], v[170:173], v[128:131]
	v_exp_f32_e32 v145, v145
	v_cvt_pk_bf16_f32 v3, v44, v45
	ds_read_b128 v[120:123], v115 offset:18432
	s_waitcnt lgkmcnt(12)
	v_mfma_f32_16x16x32_bf16 v[66:69], v[30:33], v[174:177], v[208:211]
	v_exp_f32_e32 v146, v146
	v_cvt_pk_bf16_f32 v4, v38, v39
	v_mfma_f32_16x16x32_bf16 v[78:81], v[34:37], v[174:177], v[58:61]
	v_exp_f32_e32 v147, v147
	v_cvt_pk_bf16_f32 v5, v40, v41
	ds_read_b128 v[124:127], v1 offset:20480
	s_waitcnt lgkmcnt(11)
	v_mfma_f32_16x16x32_bf16 v[70:73], v[34:37], v[216:219], v[220:223]
	v_exp_f32_e32 v148, v148
	v_mfma_f32_16x16x32_bf16 v[58:61], v[30:33], v[216:219], v[158:161]
	v_exp_f32_e32 v149, v149
	ds_read_b128 v[132:135], v115 offset:20480
	s_waitcnt lgkmcnt(10)
	v_mfma_f32_16x16x32_bf16 v[50:53], v[30:33], v[224:227], v[162:165]
	v_exp_f32_e32 v150, v150
	v_mfma_f32_16x16x32_bf16 v[62:65], v[34:37], v[224:227], v[228:231]
	v_exp_f32_e32 v151, v151
	ds_read_b128 v[128:131], v1 offset:22528
	s_waitcnt lgkmcnt(9)
	v_mfma_f32_16x16x32_bf16 v[54:57], v[34:37], v[232:235], v[236:239]
	v_exp_f32_e32 v152, v152
	v_mfma_f32_16x16x32_bf16 v[42:45], v[30:33], v[232:235], v[136:139]
	v_exp_f32_e32 v153, v153
	s_nop 1
	ds_read_b128 v[136:139], v115 offset:22528
	s_waitcnt lgkmcnt(8)
	v_mfma_f32_16x16x32_bf16 v[38:41], v[30:33], v[240:243], v[212:215]
	v_exp_f32_e32 v154, v154
	v_mfma_f32_16x16x32_bf16 v[46:49], v[34:37], v[240:243], v[244:247]
	v_exp_f32_e32 v155, v155
	v_cvt_pk_bf16_f32 v34, v140, v141
	v_cvt_pk_bf16_f32 v35, v142, v143
	v_cvt_pk_bf16_f32 v36, v148, v149
	v_cvt_pk_bf16_f32 v37, v150, v151
	v_cvt_pk_bf16_f32 v30, v144, v145
	v_cvt_pk_bf16_f32 v31, v146, v147
	v_cvt_pk_bf16_f32 v32, v152, v153
	v_cvt_pk_bf16_f32 v33, v154, v155
	s_add_i32 s33, s33, 4
	s_add_u32 s14, s14, 0x40000
	s_waitcnt vmcnt(4)
	s_barrier
	s_addc_u32 s15, s15, 0
	s_cmpk_gt_u32 s33, 0x78
	s_cbranch_scc0 .LBB0_444
; #define ATT_WAIT_BAR(N) asm volatile("s_waitcnt vmcnt(" #N ") lgkmcnt(0)\n\ts_barrier" ::: "memory")
; __device__ __forceinline__ void attn_unit_d16(const UnitDesc& U, char* shm, float lam, const float* subw) {
;     ...
;     STEP_D16(NT - 3, false, true, true, 1, 2, 0, 0, 3);   ATT_WAIT_BAR(2);
	ds_read_b64_tr_b16 v[158:159], v203
	ds_read_b64_tr_b16 v[160:161], v203 offset:2048
	s_waitcnt lgkmcnt(9)
	v_mfma_f32_16x16x32_bf16 v[140:143], v[110:113], v[10:13], 0
	s_waitcnt lgkmcnt(8)
	v_mfma_f32_16x16x32_bf16 v[152:155], v[26:29], v[14:17], v[140:143]
	ds_read_b64_tr_b16 v[162:163], v204
	ds_read_b64_tr_b16 v[164:165], v204 offset:2048
	v_mfma_f32_16x16x32_bf16 v[110:113], v[110:113], v[18:21], 0
	v_mfma_f32_16x16x32_bf16 v[144:147], v[26:29], v[22:25], v[110:113]
	ds_read_b64_tr_b16 v[166:167], v205
	ds_read_b64_tr_b16 v[168:169], v205 offset:2048
	s_waitcnt lgkmcnt(11)
	v_mfma_f32_16x16x32_bf16 v[26:29], v[116:119], v[10:13], 0
	s_waitcnt lgkmcnt(10)
	v_mfma_f32_16x16x32_bf16 v[148:151], v[120:123], v[14:17], v[26:29]
	ds_read_b64_tr_b16 v[170:171], v206
	ds_read_b64_tr_b16 v[172:173], v206 offset:2048
	v_mfma_f32_16x16x32_bf16 v[26:29], v[116:119], v[18:21], 0
	v_mfma_f32_16x16x32_bf16 v[140:143], v[120:123], v[22:25], v[26:29]
	ds_read_b64_tr_b16 v[174:175], v203 offset:8192
	ds_read_b64_tr_b16 v[176:177], v203 offset:10240
	s_waitcnt lgkmcnt(13)
	v_mfma_f32_16x16x32_bf16 v[26:29], v[124:127], v[10:13], 0
	s_waitcnt lgkmcnt(12)
	v_mfma_f32_16x16x32_bf16 v[110:113], v[132:135], v[14:17], v[26:29]
	ds_read_b64_tr_b16 v[208:209], v204 offset:8192
	ds_read_b64_tr_b16 v[210:211], v204 offset:10240
	v_mfma_f32_16x16x32_bf16 v[26:29], v[124:127], v[18:21], 0
	v_mfma_f32_16x16x32_bf16 v[116:119], v[132:135], v[22:25], v[26:29]
	ds_read_b64_tr_b16 v[132:133], v205 offset:8192
	ds_read_b64_tr_b16 v[134:135], v205 offset:10240
	s_waitcnt lgkmcnt(14)
	v_mfma_f32_16x16x32_bf16 v[26:29], v[128:131], v[10:13], 0
	v_mfma_f32_16x16x32_bf16 v[120:123], v[136:139], v[14:17], v[26:29]
	ds_read_b64_tr_b16 v[212:213], v206 offset:8192
	ds_read_b64_tr_b16 v[214:215], v206 offset:10240
	v_mfma_f32_16x16x32_bf16 v[26:29], v[128:131], v[18:21], 0
	v_mfma_f32_16x16x32_bf16 v[124:127], v[136:139], v[22:25], v[26:29]
	s_add_u32 s14, s10, 0x7f0000
	s_addc_u32 s15, s11, 0
	s_mov_b32 s28, m0
	s_mov_b32 m0, s68
	s_nop 0
	global_load_lds_dwordx4 v156, s[14:15]
	s_mov_b32 m0, s28
	s_add_u32 s10, s10, 0x7f0080
	s_addc_u32 s11, s11, 0
	s_mov_b32 s14, m0
	s_mov_b32 m0, s69
	s_nop 0
	global_load_lds_dwordx4 v156, s[10:11]
	s_mov_b32 m0, s14
	ds_read_b64_tr_b16 v[128:129], v203 offset:4096
	ds_read_b64_tr_b16 v[130:131], v203 offset:6144
	s_nop 0
	v_mov_b64_e32 v[28:29], s[6:7]
	v_mov_b64_e32 v[26:27], s[4:5]
	v_exp_f32_e32 v152, v152
	s_waitcnt lgkmcnt(14)
	v_mfma_f32_16x16x32_bf16 v[98:101], v[6:9], v[158:161], v[98:101]
	v_mfma_f32_16x16x32_bf16 v[106:109], v[6:9], v[26:29], v[106:109]
	v_exp_f32_e32 v153, v153
	v_mfma_f32_16x16x32_bf16 v[102:105], v[2:5], v[26:29], v[102:105]
	v_mfma_f32_16x16x32_bf16 v[90:93], v[2:5], v[158:161], v[90:93]
	ds_read_b64_tr_b16 v[136:137], v204 offset:4096
	ds_read_b64_tr_b16 v[138:139], v204 offset:6144
	v_exp_f32_e32 v154, v154
	v_mfma_f32_16x16x32_bf16 v[94:97], v[6:9], v[162:165], v[94:97]
	v_mfma_f32_16x16x32_bf16 v[82:85], v[2:5], v[162:165], v[82:85]
	v_exp_f32_e32 v155, v155
	ds_read_b64_tr_b16 v[156:157], v205 offset:4096
	ds_read_b64_tr_b16 v[158:159], v205 offset:6144
	v_exp_f32_e32 v144, v144
	s_waitcnt lgkmcnt(14)
	v_mfma_f32_16x16x32_bf16 v[86:89], v[6:9], v[166:169], v[86:89]
	s_nop 0
	v_exp_f32_e32 v145, v145
	v_mfma_f32_16x16x32_bf16 v[160:163], v[2:5], v[166:169], v[74:77]
	ds_read_b64_tr_b16 v[164:165], v206 offset:4096
	ds_read_b64_tr_b16 v[166:167], v206 offset:6144
	v_exp_f32_e32 v146, v146
	v_mfma_f32_16x16x32_bf16 v[216:219], v[6:9], v[170:173], v[78:81]
	s_nop 0
	v_exp_f32_e32 v147, v147
	v_mfma_f32_16x16x32_bf16 v[168:171], v[2:5], v[170:173], v[66:69]
	ds_read_b64_tr_b16 v[220:221], v203 offset:12288
	ds_read_b64_tr_b16 v[222:223], v203 offset:14336
	v_exp_f32_e32 v148, v148
	s_waitcnt lgkmcnt(14)
	v_mfma_f32_16x16x32_bf16 v[224:227], v[6:9], v[174:177], v[70:73]
	v_mfma_f32_16x16x32_bf16 v[58:61], v[2:5], v[174:177], v[58:61]
	v_exp_f32_e32 v149, v149
	ds_read_b64_tr_b16 v[172:173], v204 offset:12288
	ds_read_b64_tr_b16 v[174:175], v204 offset:14336
	v_exp_f32_e32 v150, v150
	v_mfma_f32_16x16x32_bf16 v[176:179], v[6:9], v[208:211], v[62:65]
	v_mfma_f32_16x16x32_bf16 v[50:53], v[2:5], v[208:211], v[50:53]
	v_exp_f32_e32 v151, v151
	ds_read_b64_tr_b16 v[208:209], v205 offset:12288
	ds_read_b64_tr_b16 v[210:211], v205 offset:14336
	s_waitcnt lgkmcnt(14)
	v_mfma_f32_16x16x32_bf16 v[54:57], v[6:9], v[132:135], v[54:57]
	v_exp_f32_e32 v140, v140
	v_mfma_f32_16x16x32_bf16 v[42:45], v[2:5], v[132:135], v[42:45]
	v_exp_f32_e32 v141, v141
	ds_read_b64_tr_b16 v[228:229], v206 offset:12288
	ds_read_b64_tr_b16 v[230:231], v206 offset:14336
	v_mfma_f32_16x16x32_bf16 v[46:49], v[6:9], v[212:215], v[46:49]
	v_exp_f32_e32 v142, v142
	s_nop 0
	v_exp_f32_e32 v143, v143
	v_mfma_f32_16x16x32_bf16 v[212:215], v[2:5], v[212:215], v[38:41]
	s_nop 2
	ds_read_b128 v[38:41], v1 offset:32768
	v_mfma_f32_16x16x32_bf16 v[66:69], v[34:37], v[26:29], v[106:109]
	v_exp_f32_e32 v110, v110
	v_cvt_pk_bf16_f32 v6, v152, v153
	s_waitcnt lgkmcnt(14)
	v_mfma_f32_16x16x32_bf16 v[62:65], v[34:37], v[128:131], v[98:101]
	v_mfma_f32_16x16x32_bf16 v[70:73], v[30:33], v[26:29], v[102:105]
	v_exp_f32_e32 v111, v111
	v_cvt_pk_bf16_f32 v7, v154, v155
	v_mfma_f32_16x16x32_bf16 v[78:81], v[30:33], v[128:131], v[90:93]
	ds_read_b128 v[232:235], v115 offset:32768
	s_waitcnt lgkmcnt(14)
	v_mfma_f32_16x16x32_bf16 v[74:77], v[34:37], v[136:139], v[94:97]
	v_exp_f32_e32 v112, v112
	v_cvt_pk_bf16_f32 v8, v148, v149
	v_mfma_f32_16x16x32_bf16 v[82:85], v[30:33], v[136:139], v[82:85]
	v_exp_f32_e32 v113, v113
	v_cvt_pk_bf16_f32 v9, v150, v151
	ds_read_b128 v[236:239], v1 offset:34816
	v_exp_f32_e32 v116, v116
	v_cvt_pk_bf16_f32 v2, v144, v145
	s_waitcnt lgkmcnt(13)
; #define ATT_WAIT_BAR(N) asm volatile("s_waitcnt vmcnt(" #N ") lgkmcnt(0)\n\ts_barrier" ::: "memory")
; __device__ __forceinline__ void attn_unit_d16(const UnitDesc& U, char* shm, float lam, const float* subw) {
;     ...
;     STEP_D16(NT - 3, false, true, true, 1, 2, 0, 0, 3);   ATT_WAIT_BAR(2);
;     STEP_D16(NT - 2, false, false, true, 2, 3, 1, 1, 0);  ATT_WAIT_BAR(0);
	v_mfma_f32_16x16x32_bf16 v[90:93], v[34:37], v[156:159], v[86:89]
	s_nop 0
	v_exp_f32_e32 v117, v117
	v_cvt_pk_bf16_f32 v3, v146, v147
	v_mfma_f32_16x16x32_bf16 v[94:97], v[30:33], v[156:159], v[160:163]
	ds_read_b128 v[156:159], v115 offset:34816
	v_exp_f32_e32 v118, v118
	v_cvt_pk_bf16_f32 v4, v140, v141
	s_waitcnt lgkmcnt(12)
	v_mfma_f32_16x16x32_bf16 v[98:101], v[34:37], v[164:167], v[216:219]
	s_nop 0
	v_exp_f32_e32 v119, v119
	v_cvt_pk_bf16_f32 v5, v142, v143
	v_mfma_f32_16x16x32_bf16 v[102:105], v[30:33], v[164:167], v[168:171]
	ds_read_b128 v[160:163], v1 offset:36864
	v_exp_f32_e32 v120, v120
	s_waitcnt lgkmcnt(11)
	v_mfma_f32_16x16x32_bf16 v[148:151], v[34:37], v[220:223], v[224:227]
	s_nop 0
	v_exp_f32_e32 v121, v121
	v_mfma_f32_16x16x32_bf16 v[152:155], v[30:33], v[220:223], v[58:61]
	ds_read_b128 v[164:167], v115 offset:36864
	v_exp_f32_e32 v122, v122
	s_waitcnt lgkmcnt(10)
	v_mfma_f32_16x16x32_bf16 v[140:143], v[34:37], v[172:175], v[176:179]
	s_nop 0
	v_exp_f32_e32 v123, v123
	v_mfma_f32_16x16x32_bf16 v[144:147], v[30:33], v[172:175], v[50:53]
	s_nop 2
	ds_read_b128 v[50:53], v1 offset:38912
	v_exp_f32_e32 v124, v124
	s_waitcnt lgkmcnt(9)
	v_mfma_f32_16x16x32_bf16 v[132:135], v[34:37], v[208:211], v[54:57]
	s_nop 0
	v_exp_f32_e32 v125, v125
	v_mfma_f32_16x16x32_bf16 v[136:139], v[30:33], v[208:211], v[42:45]
	ds_read_b128 v[168:171], v115 offset:38912
	v_exp_f32_e32 v126, v126
	s_waitcnt lgkmcnt(8)
	v_mfma_f32_16x16x32_bf16 v[106:109], v[34:37], v[228:231], v[46:49]
	s_nop 0
	v_exp_f32_e32 v127, v127
	v_mfma_f32_16x16x32_bf16 v[128:131], v[30:33], v[228:231], v[212:215]
	v_cvt_pk_bf16_f32 v34, v110, v111
	v_cvt_pk_bf16_f32 v35, v112, v113
	v_cvt_pk_bf16_f32 v36, v120, v121
	v_cvt_pk_bf16_f32 v37, v122, v123
	v_cvt_pk_bf16_f32 v30, v116, v117
	v_cvt_pk_bf16_f32 v31, v118, v119
	v_cvt_pk_bf16_f32 v32, v124, v125
	v_cvt_pk_bf16_f32 v33, v126, v127
	s_waitcnt vmcnt(2) lgkmcnt(0)
	s_barrier
	ds_read_b64_tr_b16 v[116:117], v203 offset:16384
	ds_read_b64_tr_b16 v[118:119], v203 offset:18432
	s_waitcnt lgkmcnt(9)
	v_mfma_f32_16x16x32_bf16 v[42:45], v[38:41], v[10:13], 0
	s_waitcnt lgkmcnt(8)
	v_mfma_f32_16x16x32_bf16 v[110:113], v[232:235], v[14:17], v[42:45]
	ds_read_b64_tr_b16 v[120:121], v204 offset:16384
	ds_read_b64_tr_b16 v[122:123], v204 offset:18432
	v_mfma_f32_16x16x32_bf16 v[38:41], v[38:41], v[18:21], 0
	v_mfma_f32_16x16x32_bf16 v[58:61], v[232:235], v[22:25], v[38:41]
	ds_read_b64_tr_b16 v[124:125], v205 offset:16384
	ds_read_b64_tr_b16 v[126:127], v205 offset:18432
	s_waitcnt lgkmcnt(11)
	v_mfma_f32_16x16x32_bf16 v[38:41], v[236:239], v[10:13], 0
	s_waitcnt lgkmcnt(10)
	v_mfma_f32_16x16x32_bf16 v[86:89], v[156:159], v[14:17], v[38:41]
	ds_read_b64_tr_b16 v[172:173], v206 offset:16384
	ds_read_b64_tr_b16 v[174:175], v206 offset:18432
	v_mfma_f32_16x16x32_bf16 v[38:41], v[236:239], v[18:21], 0
	v_mfma_f32_16x16x32_bf16 v[54:57], v[156:159], v[22:25], v[38:41]
	ds_read_b64_tr_b16 v[156:157], v203 offset:24576
	ds_read_b64_tr_b16 v[158:159], v203 offset:26624
	s_waitcnt lgkmcnt(13)
	v_mfma_f32_16x16x32_bf16 v[38:41], v[160:163], v[10:13], 0
	s_waitcnt lgkmcnt(12)
	v_mfma_f32_16x16x32_bf16 v[38:41], v[164:167], v[14:17], v[38:41]
	ds_read_b64_tr_b16 v[176:177], v204 offset:24576
	ds_read_b64_tr_b16 v[178:179], v204 offset:26624
	v_mfma_f32_16x16x32_bf16 v[42:45], v[160:163], v[18:21], 0
	v_mfma_f32_16x16x32_bf16 v[42:45], v[164:167], v[22:25], v[42:45]
	ds_read_b64_tr_b16 v[160:161], v205 offset:24576
	ds_read_b64_tr_b16 v[162:163], v205 offset:26624
	s_waitcnt lgkmcnt(14)
	v_mfma_f32_16x16x32_bf16 v[46:49], v[50:53], v[10:13], 0
	v_mfma_f32_16x16x32_bf16 v[46:49], v[168:171], v[14:17], v[46:49]
	ds_read_b64_tr_b16 v[164:165], v206 offset:24576
	ds_read_b64_tr_b16 v[166:167], v206 offset:26624
	v_mfma_f32_16x16x32_bf16 v[50:53], v[50:53], v[18:21], 0
	v_mfma_f32_16x16x32_bf16 v[50:53], v[168:171], v[22:25], v[50:53]
	ds_read_b64_tr_b16 v[168:169], v203 offset:20480
	ds_read_b64_tr_b16 v[170:171], v203 offset:22528
	v_mfma_f32_16x16x32_bf16 v[66:69], v[6:9], v[26:29], v[66:69]
	v_exp_f32_e32 v110, v110
	s_waitcnt lgkmcnt(14)
	v_mfma_f32_16x16x32_bf16 v[62:65], v[6:9], v[116:119], v[62:65]
	v_mfma_f32_16x16x32_bf16 v[70:73], v[2:5], v[26:29], v[70:73]
	v_exp_f32_e32 v111, v111
	v_mfma_f32_16x16x32_bf16 v[78:81], v[2:5], v[116:119], v[78:81]
	ds_read_b64_tr_b16 v[116:117], v204 offset:20480
	ds_read_b64_tr_b16 v[118:119], v204 offset:22528
	v_mfma_f32_16x16x32_bf16 v[74:77], v[6:9], v[120:123], v[74:77]
	v_exp_f32_e32 v112, v112
	v_mfma_f32_16x16x32_bf16 v[82:85], v[2:5], v[120:123], v[82:85]
	v_exp_f32_e32 v113, v113
	ds_read_b64_tr_b16 v[120:121], v205 offset:20480
	ds_read_b64_tr_b16 v[122:123], v205 offset:22528
	v_exp_f32_e32 v58, v58
	s_waitcnt lgkmcnt(14)
	v_mfma_f32_16x16x32_bf16 v[90:93], v[6:9], v[124:127], v[90:93]
	s_nop 0
	v_exp_f32_e32 v59, v59
	v_mfma_f32_16x16x32_bf16 v[94:97], v[2:5], v[124:127], v[94:97]
	ds_read_b64_tr_b16 v[124:125], v206 offset:20480
	ds_read_b64_tr_b16 v[126:127], v206 offset:22528
	v_exp_f32_e32 v60, v60
	v_mfma_f32_16x16x32_bf16 v[98:101], v[6:9], v[172:175], v[98:101]
	s_nop 0
	v_exp_f32_e32 v61, v61
	v_mfma_f32_16x16x32_bf16 v[102:105], v[2:5], v[172:175], v[102:105]
	ds_read_b64_tr_b16 v[172:173], v203 offset:28672
	ds_read_b64_tr_b16 v[174:175], v203 offset:30720
	v_exp_f32_e32 v86, v86
	s_waitcnt lgkmcnt(14)
; #define ATT_WAIT_BAR(N) asm volatile("s_waitcnt vmcnt(" #N ") lgkmcnt(0)\n\ts_barrier" ::: "memory")
; __device__ __forceinline__ void attn_unit_d16(const UnitDesc& U, char* shm, float lam, const float* subw) {
;     ...
;     STEP_D16(NT - 2, false, false, true, 2, 3, 1, 1, 0);  ATT_WAIT_BAR(0);
;     STEP_D16(NT - 1, false, false, false, 3, 0, 2, 2, 1); ATT_WAIT_BAR(0);
	v_mfma_f32_16x16x32_bf16 v[148:151], v[6:9], v[156:159], v[148:151]
	s_nop 0
	v_exp_f32_e32 v87, v87
	v_mfma_f32_16x16x32_bf16 v[152:155], v[2:5], v[156:159], v[152:155]
	ds_read_b64_tr_b16 v[156:157], v204 offset:28672
	ds_read_b64_tr_b16 v[158:159], v204 offset:30720
	v_exp_f32_e32 v88, v88
	v_mfma_f32_16x16x32_bf16 v[140:143], v[6:9], v[176:179], v[140:143]
	s_nop 0
	v_exp_f32_e32 v89, v89
	v_mfma_f32_16x16x32_bf16 v[144:147], v[2:5], v[176:179], v[144:147]
	ds_read_b64_tr_b16 v[176:177], v205 offset:28672
	ds_read_b64_tr_b16 v[178:179], v205 offset:30720
	v_exp_f32_e32 v54, v54
	s_waitcnt lgkmcnt(14)
	v_mfma_f32_16x16x32_bf16 v[208:211], v[6:9], v[160:163], v[132:135]
	s_nop 0
	v_exp_f32_e32 v55, v55
	v_mfma_f32_16x16x32_bf16 v[160:163], v[2:5], v[160:163], v[136:139]
	ds_read_b64_tr_b16 v[212:213], v206 offset:28672
	ds_read_b64_tr_b16 v[214:215], v206 offset:30720
	v_exp_f32_e32 v56, v56
	v_mfma_f32_16x16x32_bf16 v[216:219], v[6:9], v[164:167], v[106:109]
	s_nop 0
	v_exp_f32_e32 v57, v57
	v_mfma_f32_16x16x32_bf16 v[164:167], v[2:5], v[164:167], v[128:131]
	ds_read_b128 v[136:139], v1 offset:49152
	v_mfma_f32_16x16x32_bf16 v[66:69], v[34:37], v[26:29], v[66:69]
	v_exp_f32_e32 v38, v38
	v_cvt_pk_bf16_f32 v6, v110, v111
	s_waitcnt lgkmcnt(14)
	v_mfma_f32_16x16x32_bf16 v[62:65], v[34:37], v[168:171], v[62:65]
	v_mfma_f32_16x16x32_bf16 v[70:73], v[30:33], v[26:29], v[70:73]
	v_exp_f32_e32 v39, v39
	v_cvt_pk_bf16_f32 v7, v112, v113
	v_mfma_f32_16x16x32_bf16 v[78:81], v[30:33], v[168:171], v[78:81]
	ds_read_b128 v[168:171], v115 offset:49152
	s_waitcnt lgkmcnt(14)
	v_mfma_f32_16x16x32_bf16 v[74:77], v[34:37], v[116:119], v[74:77]
	v_exp_f32_e32 v40, v40
	v_cvt_pk_bf16_f32 v8, v86, v87
	v_mfma_f32_16x16x32_bf16 v[82:85], v[30:33], v[116:119], v[82:85]
	v_exp_f32_e32 v41, v41
	v_cvt_pk_bf16_f32 v9, v88, v89
	ds_read_b128 v[220:223], v1 offset:51200
	v_exp_f32_e32 v42, v42
	v_cvt_pk_bf16_f32 v2, v58, v59
	s_waitcnt lgkmcnt(13)
	v_mfma_f32_16x16x32_bf16 v[86:89], v[34:37], v[120:123], v[90:93]
	s_nop 0
	v_exp_f32_e32 v43, v43
	v_cvt_pk_bf16_f32 v3, v60, v61
	v_mfma_f32_16x16x32_bf16 v[90:93], v[30:33], v[120:123], v[94:97]
	ds_read_b128 v[224:227], v115 offset:51200
	s_waitcnt lgkmcnt(12)
	v_mfma_f32_16x16x32_bf16 v[58:61], v[34:37], v[124:127], v[98:101]
	v_exp_f32_e32 v44, v44
	v_cvt_pk_bf16_f32 v4, v54, v55
	s_nop 0
	v_exp_f32_e32 v45, v45
	v_cvt_pk_bf16_f32 v5, v56, v57
	v_mfma_f32_16x16x32_bf16 v[94:97], v[30:33], v[124:127], v[102:105]
	ds_read_b128 v[228:231], v1 offset:53248
	v_exp_f32_e32 v46, v46
	s_waitcnt lgkmcnt(11)
	v_mfma_f32_16x16x32_bf16 v[128:131], v[34:37], v[172:175], v[148:151]
	s_nop 0
	v_exp_f32_e32 v47, v47
	v_mfma_f32_16x16x32_bf16 v[132:135], v[30:33], v[172:175], v[152:155]
	ds_read_b128 v[148:151], v115 offset:53248
	v_exp_f32_e32 v48, v48
	s_waitcnt lgkmcnt(10)
	v_mfma_f32_16x16x32_bf16 v[120:123], v[34:37], v[156:159], v[140:143]
	s_nop 0
	v_exp_f32_e32 v49, v49
	v_mfma_f32_16x16x32_bf16 v[124:127], v[30:33], v[156:159], v[144:147]
	ds_read_b128 v[140:143], v1 offset:55296
	v_exp_f32_e32 v50, v50
	s_waitcnt lgkmcnt(9)
	v_mfma_f32_16x16x32_bf16 v[106:109], v[34:37], v[176:179], v[208:211]
	s_nop 0
	v_exp_f32_e32 v51, v51
	v_mfma_f32_16x16x32_bf16 v[110:113], v[30:33], v[176:179], v[160:163]
	ds_read_b128 v[144:147], v115 offset:55296
	v_exp_f32_e32 v52, v52
	s_waitcnt lgkmcnt(8)
	v_mfma_f32_16x16x32_bf16 v[98:101], v[34:37], v[212:215], v[216:219]
	s_nop 0
	v_exp_f32_e32 v53, v53
	v_mfma_f32_16x16x32_bf16 v[102:105], v[30:33], v[212:215], v[164:167]
	v_cvt_pk_bf16_f32 v34, v38, v39
	v_cvt_pk_bf16_f32 v35, v40, v41
	v_cvt_pk_bf16_f32 v36, v46, v47
	v_cvt_pk_bf16_f32 v37, v48, v49
	v_cvt_pk_bf16_f32 v30, v42, v43
	v_cvt_pk_bf16_f32 v31, v44, v45
	v_cvt_pk_bf16_f32 v32, v50, v51
	v_cvt_pk_bf16_f32 v33, v52, v53
	s_waitcnt vmcnt(0) lgkmcnt(0)
	s_barrier
	ds_read_b64_tr_b16 v[152:153], v203 offset:32768
	ds_read_b64_tr_b16 v[154:155], v203 offset:34816
	s_waitcnt lgkmcnt(9)
	v_mfma_f32_16x16x32_bf16 v[38:41], v[136:139], v[10:13], 0
	s_waitcnt lgkmcnt(8)
	v_mfma_f32_16x16x32_bf16 v[116:119], v[168:171], v[14:17], v[38:41]
	ds_read_b64_tr_b16 v[156:157], v204 offset:32768
	ds_read_b64_tr_b16 v[158:159], v204 offset:34816
	v_mfma_f32_16x16x32_bf16 v[38:41], v[136:139], v[18:21], 0
	v_mfma_f32_16x16x32_bf16 v[50:53], v[168:171], v[22:25], v[38:41]
	ds_read_b64_tr_b16 v[136:137], v205 offset:32768
	ds_read_b64_tr_b16 v[138:139], v205 offset:34816
	s_waitcnt lgkmcnt(11)
	v_mfma_f32_16x16x32_bf16 v[38:41], v[220:223], v[10:13], 0
	s_waitcnt lgkmcnt(10)
	v_mfma_f32_16x16x32_bf16 v[54:57], v[224:227], v[14:17], v[38:41]
	ds_read_b64_tr_b16 v[160:161], v206 offset:32768
	ds_read_b64_tr_b16 v[162:163], v206 offset:34816
	v_mfma_f32_16x16x32_bf16 v[38:41], v[220:223], v[18:21], 0
	v_mfma_f32_16x16x32_bf16 v[46:49], v[224:227], v[22:25], v[38:41]
	ds_read_b64_tr_b16 v[164:165], v203 offset:40960
	ds_read_b64_tr_b16 v[166:167], v203 offset:43008
	s_waitcnt lgkmcnt(13)
	v_mfma_f32_16x16x32_bf16 v[38:41], v[228:231], v[10:13], 0
	s_waitcnt lgkmcnt(12)
	v_mfma_f32_16x16x32_bf16 v[38:41], v[148:151], v[14:17], v[38:41]
	ds_read_b64_tr_b16 v[168:169], v204 offset:40960
	ds_read_b64_tr_b16 v[170:171], v204 offset:43008
	v_mfma_f32_16x16x32_bf16 v[42:45], v[228:231], v[18:21], 0
	v_mfma_f32_16x16x32_bf16 v[42:45], v[148:151], v[22:25], v[42:45]
	ds_read_b64_tr_b16 v[148:149], v205 offset:40960
	ds_read_b64_tr_b16 v[150:151], v205 offset:43008
	s_waitcnt lgkmcnt(14)
; #define ATT_WAIT_BAR(N) asm volatile("s_waitcnt vmcnt(" #N ") lgkmcnt(0)\n\ts_barrier" ::: "memory")
; __device__ __forceinline__ void attn_unit_d16(const UnitDesc& U, char* shm, float lam, const float* subw) {
;     ...
;     STEP_D16(NT - 1, false, false, false, 3, 0, 2, 2, 1); ATT_WAIT_BAR(0);
	v_mfma_f32_16x16x32_bf16 v[10:13], v[140:143], v[10:13], 0
	v_mfma_f32_16x16x32_bf16 v[10:13], v[144:147], v[14:17], v[10:13]
	ds_read_b64_tr_b16 v[172:173], v206 offset:40960
	ds_read_b64_tr_b16 v[174:175], v206 offset:43008
	v_mfma_f32_16x16x32_bf16 v[14:17], v[140:143], v[18:21], 0
	v_mfma_f32_16x16x32_bf16 v[14:17], v[144:147], v[22:25], v[14:17]
	ds_read_b64_tr_b16 v[140:141], v203 offset:36864
	ds_read_b64_tr_b16 v[142:143], v203 offset:38912
	v_mfma_f32_16x16x32_bf16 v[18:21], v[6:9], v[26:29], v[66:69]
	v_exp_f32_e32 v116, v116
	s_waitcnt lgkmcnt(14)
	v_mfma_f32_16x16x32_bf16 v[22:25], v[6:9], v[152:155], v[62:65]
	v_mfma_f32_16x16x32_bf16 v[62:65], v[2:5], v[26:29], v[70:73]
	v_exp_f32_e32 v117, v117
	v_mfma_f32_16x16x32_bf16 v[66:69], v[2:5], v[152:155], v[78:81]
	s_nop 0
	ds_read_b64_tr_b16 v[70:71], v204 offset:36864
	ds_read_b64_tr_b16 v[72:73], v204 offset:38912
	v_mfma_f32_16x16x32_bf16 v[74:77], v[6:9], v[156:159], v[74:77]
	v_exp_f32_e32 v118, v118
	v_mfma_f32_16x16x32_bf16 v[78:81], v[2:5], v[156:159], v[82:85]
	v_exp_f32_e32 v119, v119
	s_nop 1
	ds_read_b64_tr_b16 v[82:83], v205 offset:36864
	ds_read_b64_tr_b16 v[84:85], v205 offset:38912
	v_exp_f32_e32 v50, v50
	s_waitcnt lgkmcnt(14)
	v_mfma_f32_16x16x32_bf16 v[86:89], v[6:9], v[136:139], v[86:89]
	s_nop 0
	v_exp_f32_e32 v51, v51
	v_mfma_f32_16x16x32_bf16 v[90:93], v[2:5], v[136:139], v[90:93]
	ds_read_b64_tr_b16 v[136:137], v206 offset:36864
	ds_read_b64_tr_b16 v[138:139], v206 offset:38912
	v_exp_f32_e32 v52, v52
	v_mfma_f32_16x16x32_bf16 v[144:147], v[6:9], v[160:163], v[58:61]
	s_nop 0
	v_exp_f32_e32 v53, v53
	v_mfma_f32_16x16x32_bf16 v[94:97], v[2:5], v[160:163], v[94:97]
	ds_read_b64_tr_b16 v[152:153], v203 offset:45056
	ds_read_b64_tr_b16 v[154:155], v203 offset:47104
	v_exp_f32_e32 v54, v54
	s_waitcnt lgkmcnt(14)
	v_mfma_f32_16x16x32_bf16 v[128:131], v[6:9], v[164:167], v[128:131]
	s_nop 0
	v_exp_f32_e32 v55, v55
	v_mfma_f32_16x16x32_bf16 v[132:135], v[2:5], v[164:167], v[132:135]
	ds_read_b64_tr_b16 v[156:157], v204 offset:45056
	ds_read_b64_tr_b16 v[158:159], v204 offset:47104
	v_exp_f32_e32 v56, v56
	v_mfma_f32_16x16x32_bf16 v[120:123], v[6:9], v[168:171], v[120:123]
	s_nop 0
	v_exp_f32_e32 v57, v57
	v_mfma_f32_16x16x32_bf16 v[124:127], v[2:5], v[168:171], v[124:127]
	ds_read_b64_tr_b16 v[160:161], v205 offset:45056
	ds_read_b64_tr_b16 v[162:163], v205 offset:47104
	v_exp_f32_e32 v46, v46
	s_waitcnt lgkmcnt(14)
	v_mfma_f32_16x16x32_bf16 v[106:109], v[6:9], v[148:151], v[106:109]
	s_nop 0
	v_exp_f32_e32 v47, v47
	v_mfma_f32_16x16x32_bf16 v[110:113], v[2:5], v[148:151], v[110:113]
	ds_read_b64_tr_b16 v[148:149], v206 offset:45056
	ds_read_b64_tr_b16 v[150:151], v206 offset:47104
	v_exp_f32_e32 v48, v48
	v_mfma_f32_16x16x32_bf16 v[98:101], v[6:9], v[172:175], v[98:101]
	s_nop 0
	v_exp_f32_e32 v49, v49
	v_mfma_f32_16x16x32_bf16 v[102:105], v[2:5], v[172:175], v[102:105]
	v_mfma_f32_16x16x32_bf16 v[18:21], v[34:37], v[26:29], v[18:21]
	v_exp_f32_e32 v38, v38
	v_cvt_pk_bf16_f32 v6, v116, v117
	s_waitcnt lgkmcnt(14)
	v_mfma_f32_16x16x32_bf16 v[58:61], v[34:37], v[140:143], v[22:25]
	v_mfma_f32_16x16x32_bf16 v[66:69], v[30:33], v[140:143], v[66:69]
	v_exp_f32_e32 v39, v39
	v_cvt_pk_bf16_f32 v7, v118, v119
	v_mfma_f32_16x16x32_bf16 v[22:25], v[30:33], v[26:29], v[62:65]
	s_waitcnt lgkmcnt(12)
	v_mfma_f32_16x16x32_bf16 v[62:65], v[34:37], v[70:73], v[74:77]
	v_exp_f32_e32 v40, v40
	v_cvt_pk_bf16_f32 v8, v54, v55
	v_mfma_f32_16x16x32_bf16 v[70:73], v[30:33], v[70:73], v[78:81]
	v_exp_f32_e32 v41, v41
	v_cvt_pk_bf16_f32 v9, v56, v57
	s_waitcnt lgkmcnt(10)
	v_mfma_f32_16x16x32_bf16 v[54:57], v[34:37], v[82:85], v[86:89]
	v_exp_f32_e32 v42, v42
	v_cvt_pk_bf16_f32 v2, v50, v51
	v_mfma_f32_16x16x32_bf16 v[74:77], v[30:33], v[82:85], v[90:93]
	v_exp_f32_e32 v43, v43
	v_cvt_pk_bf16_f32 v3, v52, v53
	s_waitcnt lgkmcnt(8)
	v_mfma_f32_16x16x32_bf16 v[50:53], v[34:37], v[136:139], v[144:147]
	v_exp_f32_e32 v44, v44
	v_cvt_pk_bf16_f32 v4, v46, v47
	v_mfma_f32_16x16x32_bf16 v[78:81], v[30:33], v[136:139], v[94:97]
	v_exp_f32_e32 v45, v45
	v_cvt_pk_bf16_f32 v5, v48, v49
	s_waitcnt lgkmcnt(6)
	v_mfma_f32_16x16x32_bf16 v[46:49], v[34:37], v[152:155], v[128:131]
	v_exp_f32_e32 v10, v10
	v_mfma_f32_16x16x32_bf16 v[82:85], v[30:33], v[152:155], v[132:135]
	v_exp_f32_e32 v11, v11
	s_nop 0
	v_exp_f32_e32 v12, v12
	s_waitcnt lgkmcnt(4)
	v_mfma_f32_16x16x32_bf16 v[86:89], v[34:37], v[156:159], v[120:123]
	s_nop 0
	v_exp_f32_e32 v13, v13
	v_mfma_f32_16x16x32_bf16 v[90:93], v[30:33], v[156:159], v[124:127]
	v_exp_f32_e32 v14, v14
	s_waitcnt lgkmcnt(2)
	v_mfma_f32_16x16x32_bf16 v[94:97], v[34:37], v[160:163], v[106:109]
	s_nop 0
	v_exp_f32_e32 v15, v15
	v_mfma_f32_16x16x32_bf16 v[106:109], v[30:33], v[160:163], v[110:113]
	s_waitcnt lgkmcnt(0)
	v_mfma_f32_16x16x32_bf16 v[34:37], v[34:37], v[148:151], v[98:101]
	v_exp_f32_e32 v16, v16
	v_mfma_f32_16x16x32_bf16 v[30:33], v[30:33], v[148:151], v[102:105]
	v_exp_f32_e32 v17, v17
	v_cvt_pk_bf16_f32 v98, v38, v39
	v_cvt_pk_bf16_f32 v99, v40, v41
	v_cvt_pk_bf16_f32 v100, v10, v11
	v_cvt_pk_bf16_f32 v101, v12, v13
	v_cvt_pk_bf16_f32 v102, v42, v43
	v_cvt_pk_bf16_f32 v103, v44, v45
	v_cvt_pk_bf16_f32 v104, v14, v15
	v_cvt_pk_bf16_f32 v105, v16, v17
	s_waitcnt vmcnt(0) lgkmcnt(0)
	s_barrier
; #define ATT_WAIT_BAR(N) asm volatile("s_waitcnt vmcnt(" #N ") lgkmcnt(0)\n\ts_barrier" ::: "memory")
; #define MF16(a, b, c) __builtin_amdgcn_mfma_f32_16x16x32_bf16(a, b, c, 0, 0, 0)
; #define MF16(a, b, c) __builtin_amdgcn_mfma_f32_16x16x32_bf16(a, b, c, 0, 0, 0)
; #define VRD16(f) do { vlo[f] = vtr(vpb[(f) & 3] + vo_ + (((f) >> 2) & 1) * 8192 + ((f) >> 3) * 4096); vhi[f] = vtr(vpb[(f) & 3] + vo_ + (((f) >> 2) & 1) * 8192 + ((f) >> 3) * 4096 + 2048); } while (0)
; __device__ __forceinline__ void attn_unit_d16(const UnitDesc& U, char* shm, float lam, const float* subw) {
;     ...
;     STEP_D16(NT - 1, false, false, false, 3, 0, 2, 2, 1); ATT_WAIT_BAR(0);
;     { constexpr int vo_ = 3 * VS;
; #pragma unroll
;       for (int f = 0; f < 16; ++f) { VRD16(f);
; #pragma unroll
;           for (int qt = 0; qt < 2; ++qt) o[qt][f & 7] = MF16(__builtin_bit_cast(bf16x8, pa[qt][f >> 3]), VFR16(f), o[qt][f & 7]); }
; #pragma unroll
;       for (int qt = 0; qt < 2; ++qt)
; #pragma unroll
;           for (int ks = 0; ks < 2; ++ks) ls[qt] = MF16(__builtin_bit_cast(bf16x8, pa[qt][ks]), onesb, ls[qt]); }
;     int lane_e = lane; asm volatile("" : "+v"(lane_e));
;     const int c16_e = lane_e & 15, g_e = lane_e >> 4;
;     asm volatile("s_waitcnt lgkmcnt(0)\n\ts_barrier" ::: "memory");
;     float* X = (float*)shm + (wid & 3) * 4096;
;     if (wid >= 4) {
; #pragma unroll
;         for (int qt = 0; qt < 2; ++qt)
; #pragma unroll
;             for (int r = 0; r < 4; ++r) { const float sc = __builtin_amdgcn_rcpf(ls[qt][r]) * lam; const int row = 16 * qt + 4 * g_e + r;
	ds_read_b64_tr_b16 v[10:11], v203 offset:49152
	ds_read_b64_tr_b16 v[12:13], v203 offset:51200
	ds_read_b64_tr_b16 v[14:15], v203 offset:53248
	ds_read_b64_tr_b16 v[16:17], v203 offset:55296
	v_mov_b32_e32 v1, v193
	s_lshl_b32 s10, s13, 14
	s_waitcnt lgkmcnt(2)
	v_mfma_f32_16x16x32_bf16 v[38:41], v[6:9], v[10:13], v[58:61]
	ds_read_b64_tr_b16 v[42:43], v204 offset:49152
	ds_read_b64_tr_b16 v[44:45], v204 offset:51200
	s_nop 0
	ds_read_b64_tr_b16 v[58:59], v204 offset:53248
	ds_read_b64_tr_b16 v[60:61], v204 offset:55296
	s_and_b32 s10, s10, 0xc000
	s_add_i32 s10, s10, 0
	v_mfma_f32_16x16x32_bf16 v[10:13], v[2:5], v[10:13], v[66:69]
	s_nop 2
	ds_read_b64_tr_b16 v[66:67], v205 offset:49152
	ds_read_b64_tr_b16 v[68:69], v205 offset:51200
	ds_read_b64_tr_b16 v[110:111], v205 offset:53248
	ds_read_b64_tr_b16 v[112:113], v205 offset:55296
	s_cmpk_gt_u32 s12, 0xff
	s_waitcnt lgkmcnt(6)
	v_mfma_f32_16x16x32_bf16 v[62:65], v[6:9], v[42:45], v[62:65]
	v_mfma_f32_16x16x32_bf16 v[42:45], v[2:5], v[42:45], v[70:73]
	s_nop 2
	ds_read_b64_tr_b16 v[70:71], v206 offset:49152
	ds_read_b64_tr_b16 v[72:73], v206 offset:51200
	ds_read_b64_tr_b16 v[116:117], v206 offset:53248
	ds_read_b64_tr_b16 v[118:119], v206 offset:55296
	s_waitcnt lgkmcnt(2)
	v_mfma_f32_16x16x32_bf16 v[50:53], v[6:9], v[70:73], v[50:53]
	v_mfma_f32_16x16x32_bf16 v[78:81], v[2:5], v[70:73], v[78:81]
	ds_read_b64_tr_b16 v[70:71], v203 offset:57344
	ds_read_b64_tr_b16 v[72:73], v203 offset:59392
	ds_read_b64_tr_b16 v[120:121], v203 offset:61440
	ds_read_b64_tr_b16 v[122:123], v203 offset:63488
	s_waitcnt lgkmcnt(2)
	v_mfma_f32_16x16x32_bf16 v[46:49], v[6:9], v[70:73], v[46:49]
	v_mfma_f32_16x16x32_bf16 v[82:85], v[2:5], v[70:73], v[82:85]
	ds_read_b64_tr_b16 v[70:71], v204 offset:57344
	ds_read_b64_tr_b16 v[72:73], v204 offset:59392
	ds_read_b64_tr_b16 v[124:125], v204 offset:61440
	ds_read_b64_tr_b16 v[126:127], v204 offset:63488
	s_waitcnt lgkmcnt(2)
	v_mfma_f32_16x16x32_bf16 v[86:89], v[6:9], v[70:73], v[86:89]
	v_mfma_f32_16x16x32_bf16 v[90:93], v[2:5], v[70:73], v[90:93]
	ds_read_b64_tr_b16 v[70:71], v205 offset:57344
	ds_read_b64_tr_b16 v[72:73], v205 offset:59392
	ds_read_b64_tr_b16 v[128:129], v205 offset:61440
	ds_read_b64_tr_b16 v[130:131], v205 offset:63488
	s_waitcnt lgkmcnt(2)
	v_mfma_f32_16x16x32_bf16 v[94:97], v[6:9], v[70:73], v[94:97]
	v_mfma_f32_16x16x32_bf16 v[106:109], v[2:5], v[70:73], v[106:109]
	ds_read_b64_tr_b16 v[70:71], v206 offset:57344
	ds_read_b64_tr_b16 v[72:73], v206 offset:59392
	ds_read_b64_tr_b16 v[132:133], v206 offset:61440
	ds_read_b64_tr_b16 v[134:135], v206 offset:63488
	s_waitcnt lgkmcnt(0)
	s_barrier
	v_mfma_f32_16x16x32_bf16 v[54:57], v[6:9], v[66:69], v[54:57]
	v_mfma_f32_16x16x32_bf16 v[66:69], v[2:5], v[66:69], v[74:77]
	s_waitcnt lgkmcnt(2)
	v_mfma_f32_16x16x32_bf16 v[136:139], v[6:9], v[70:73], v[34:37]
	v_mfma_f32_16x16x32_bf16 v[140:143], v[2:5], v[70:73], v[30:33]
	v_mfma_f32_16x16x32_bf16 v[6:9], v[6:9], v[26:29], v[18:21]
	v_mfma_f32_16x16x32_bf16 v[2:5], v[2:5], v[26:29], v[22:25]
	v_mfma_f32_16x16x32_bf16 v[74:77], v[98:101], v[58:61], v[62:65]
	v_mfma_f32_16x16x32_bf16 v[42:45], v[102:105], v[58:61], v[42:45]
	v_mfma_f32_16x16x32_bf16 v[58:61], v[98:101], v[110:113], v[54:57]
	v_mfma_f32_16x16x32_bf16 v[54:57], v[98:101], v[124:127], v[86:89]
	v_mfma_f32_16x16x32_bf16 v[86:89], v[98:101], v[26:29], v[6:9]
	v_mfma_f32_16x16x32_bf16 v[2:5], v[102:105], v[26:29], v[2:5]
	v_mfma_f32_16x16x32_bf16 v[70:73], v[98:101], v[14:17], v[38:41]
	s_nop 5
	v_rcp_f32_e32 v21, v86
	v_rcp_f32_e32 v20, v87
	v_rcp_f32_e32 v19, v88
	v_mfma_f32_16x16x32_bf16 v[38:41], v[102:105], v[14:17], v[10:13]
	v_rcp_f32_e32 v18, v89
	v_rcp_f32_e32 v9, v2
	v_rcp_f32_e32 v8, v3
	v_mfma_f32_16x16x32_bf16 v[10:13], v[102:105], v[120:123], v[82:85]
	s_nop 2
	v_and_b32_e32 v84, 15, v1
	v_ashrrev_i32_e32 v82, 4, v1
	v_lshlrev_b32_e32 v1, 11, v82
	v_lshlrev_b32_e32 v6, 2, v84
	v_mfma_f32_16x16x32_bf16 v[30:33], v[102:105], v[110:113], v[66:69]
	v_add3_u32 v7, s10, v6, v1
	v_rcp_f32_e32 v6, v4
	v_rcp_f32_e32 v1, v5
	v_mfma_f32_16x16x32_bf16 v[62:65], v[98:101], v[116:119], v[50:53]
	v_mfma_f32_16x16x32_bf16 v[34:37], v[102:105], v[116:119], v[78:81]
	v_mfma_f32_16x16x32_bf16 v[66:69], v[98:101], v[120:123], v[46:49]
	v_mfma_f32_16x16x32_bf16 v[14:17], v[102:105], v[124:127], v[90:93]
	v_mfma_f32_16x16x32_bf16 v[50:53], v[98:101], v[128:131], v[94:97]
	v_mfma_f32_16x16x32_bf16 v[46:49], v[102:105], v[128:131], v[106:109]
	s_waitcnt lgkmcnt(0)
	v_mfma_f32_16x16x32_bf16 v[78:81], v[98:101], v[132:135], v[136:139]
	v_mfma_f32_16x16x32_bf16 v[2:5], v[102:105], v[132:135], v[140:143]
	s_cbranch_scc0 .LBB0_447
; __device__ __forceinline__ void attn_unit_d16(const UnitDesc& U, char* shm, float lam, const float* subw) {
;     ...
;     if (wid >= 4) {
; #pragma unroll
;         for (int qt = 0; qt < 2; ++qt)
; #pragma unroll
;             for (int r = 0; r < 4; ++r) { const float sc = __builtin_amdgcn_rcpf(ls[qt][r]) * lam; const int row = 16 * qt + 4 * g_e + r;
; #pragma unroll
;                 for (int dt = 0; dt < 8; ++dt) X[row * 128 + 16 * dt + c16_e] = o[qt][dt][r] * sc; }
;     }
	v_mul_f32_e32 v22, v181, v21
	v_mul_f32_e32 v23, v70, v22
	v_mul_f32_e32 v24, v74, v22
	ds_write2_b32 v7, v23, v24 offset1:16
	v_mul_f32_e32 v23, v58, v22
	v_mul_f32_e32 v24, v62, v22
	ds_write2_b32 v7, v23, v24 offset0:32 offset1:48
	v_mul_f32_e32 v23, v66, v22
	v_mul_f32_e32 v24, v54, v22
	ds_write2_b32 v7, v23, v24 offset0:64 offset1:80
	v_mul_f32_e32 v23, v50, v22
	v_mul_f32_e32 v22, v78, v22
	ds_write2_b32 v7, v23, v22 offset0:96 offset1:112
	v_mul_f32_e32 v22, v181, v20
	v_mul_f32_e32 v23, v71, v22
	v_mul_f32_e32 v24, v75, v22
	ds_write2_b32 v7, v23, v24 offset0:128 offset1:144
	v_mul_f32_e32 v23, v59, v22
	v_mul_f32_e32 v24, v63, v22
	ds_write2_b32 v7, v23, v24 offset0:160 offset1:176
	v_mul_f32_e32 v23, v67, v22
	v_mul_f32_e32 v24, v55, v22
	ds_write2_b32 v7, v23, v24 offset0:192 offset1:208
	v_mul_f32_e32 v23, v51, v22
	v_mul_f32_e32 v22, v79, v22
	ds_write2_b32 v7, v23, v22 offset0:224 offset1:240
	v_mul_f32_e32 v22, v181, v19
	v_mul_f32_e32 v23, v72, v22
	v_mul_f32_e32 v24, v76, v22
	v_add_u32_e32 v25, 0x400, v7
	ds_write2_b32 v25, v23, v24 offset1:16
	v_mul_f32_e32 v23, v60, v22
	v_mul_f32_e32 v24, v64, v22
	ds_write2_b32 v25, v23, v24 offset0:32 offset1:48
	v_mul_f32_e32 v23, v68, v22
	v_mul_f32_e32 v24, v56, v22
	ds_write2_b32 v25, v23, v24 offset0:64 offset1:80
	v_mul_f32_e32 v23, v52, v22
	v_mul_f32_e32 v22, v80, v22
	ds_write2_b32 v25, v23, v22 offset0:96 offset1:112
	v_mul_f32_e32 v22, v181, v18
	v_mul_f32_e32 v23, v73, v22
	v_mul_f32_e32 v24, v77, v22
	ds_write2_b32 v25, v23, v24 offset0:128 offset1:144
	v_mul_f32_e32 v23, v61, v22
	v_mul_f32_e32 v24, v65, v22
	ds_write2_b32 v25, v23, v24 offset0:160 offset1:176
	v_mul_f32_e32 v23, v69, v22
	v_mul_f32_e32 v24, v57, v22
	ds_write2_b32 v25, v23, v24 offset0:192 offset1:208
	v_mul_f32_e32 v23, v53, v22
	v_mul_f32_e32 v22, v81, v22
	ds_write2_b32 v25, v23, v22 offset0:224 offset1:240
	v_mul_f32_e32 v22, v181, v9
	v_mul_f32_e32 v23, v38, v22
	v_mul_f32_e32 v24, v42, v22
	v_add_u32_e32 v25, 0x2000, v7
	ds_write2_b32 v25, v23, v24 offset1:16
	v_mul_f32_e32 v23, v30, v22
	v_mul_f32_e32 v24, v34, v22
	ds_write2_b32 v25, v23, v24 offset0:32 offset1:48
	v_mul_f32_e32 v23, v10, v22
	v_mul_f32_e32 v24, v14, v22
	ds_write2_b32 v25, v23, v24 offset0:64 offset1:80
	v_mul_f32_e32 v23, v46, v22
	v_mul_f32_e32 v22, v2, v22
	ds_write2_b32 v25, v23, v22 offset0:96 offset1:112
	v_mul_f32_e32 v22, v181, v8
	v_mul_f32_e32 v23, v39, v22
	v_mul_f32_e32 v24, v43, v22
	ds_write2_b32 v25, v23, v24 offset0:128 offset1:144
	v_mul_f32_e32 v23, v31, v22
	v_mul_f32_e32 v24, v35, v22
	ds_write2_b32 v25, v23, v24 offset0:160 offset1:176
	v_mul_f32_e32 v23, v11, v22
	v_mul_f32_e32 v24, v15, v22
	ds_write2_b32 v25, v23, v24 offset0:192 offset1:208
	v_mul_f32_e32 v23, v47, v22
	v_mul_f32_e32 v22, v3, v22
	ds_write2_b32 v25, v23, v22 offset0:224 offset1:240
	v_mul_f32_e32 v22, v181, v6
	v_mul_f32_e32 v23, v40, v22
	v_mul_f32_e32 v24, v44, v22
	v_add_u32_e32 v25, 0x2400, v7
	ds_write2_b32 v25, v23, v24 offset1:16
	v_mul_f32_e32 v23, v32, v22
	v_mul_f32_e32 v24, v36, v22
	ds_write2_b32 v25, v23, v24 offset0:32 offset1:48
	v_mul_f32_e32 v23, v12, v22
	v_mul_f32_e32 v24, v16, v22
	ds_write2_b32 v25, v23, v24 offset0:64 offset1:80
	v_mul_f32_e32 v23, v48, v22
	v_mul_f32_e32 v22, v4, v22
	ds_write2_b32 v25, v23, v22 offset0:96 offset1:112
	v_mul_f32_e32 v22, v181, v1
	v_mul_f32_e32 v23, v41, v22
	v_mul_f32_e32 v24, v45, v22
	ds_write2_b32 v25, v23, v24 offset0:128 offset1:144
	v_mul_f32_e32 v23, v33, v22
	v_mul_f32_e32 v24, v37, v22
	ds_write2_b32 v25, v23, v24 offset0:160 offset1:176
	v_mul_f32_e32 v23, v13, v22
	v_mul_f32_e32 v24, v17, v22
	ds_write2_b32 v25, v23, v24 offset0:192 offset1:208
	v_mul_f32_e32 v23, v49, v22
	v_mul_f32_e32 v22, v5, v22
	ds_write2_b32 v25, v23, v22 offset0:224 offset1:240
